# dense attention K/V tiles staged by LDS-DMA (global_load_lds_dwordx4, swizzle on the source address, landing one interval after issue) instead of register staging plus ds_write
# speedup vs baseline: 1.0202x; 1.0173x over previous
; __device__ __forceinline__ int v_st(int k, int c) { const int kk = (k & ~0xC) | ((k & 4) << 1) | ((k & 8) >> 1); return ((kk >> 3) * 4 + (c >> 5)) * 512 + ((kk & 7) * 32 + (c & 31)) * 2; }
; __device__ __forceinline__ int v_rd_base(int lane) { return ((lane & 3) << 3) | (((lane >> 2) & 3) << 6) | (((lane >> 4) & 1) << 5) | (((lane >> 5) & 1) << 8); }
;     ...
;   const int sr = tid >> 4, sc = (tid & 15) * 8, vst0 = v_st(sr, sc), vst1 = vst0 + 8192;
;   const int vb0 = (int)(uintptr_t)V_lds + v_rd_base(lane);
;   const int qrel = wid * QBLK + r32;
;   constexpr int SD = (MODE == 0) ? ATT_SD0 : 2;
;   struct { bf16x8 vs0, vs1, ks0, ks1; } sr_[SD];
;   const unsigned soff0 = (unsigned)(sr * (int)ldk + sc) * 2u, soff1 = soff0 + (unsigned)(32 * (int)ldk) * 2u;
;     ...
;   PLOAD(0); asm volatile("s_waitcnt vmcnt(0)" ::: "memory"); PWRITE(0); __syncthreads();
.LBB0_486:
	v_and_b32_e32 v64, 63, v218
	v_and_b32_e32 v65, 15, v64
	v_lshrrev_b32_e32 v66, 4, v64
	v_add_u32_e32 v67, 0, v66
	v_xor_b32_e32 v67, v67, v65
	v_lshlrev_b32_e32 v67, 4, v67
	v_lshl_or_b32 v172, v65, 8, v67
	v_add_u32_e32 v67, 4, v66
	v_xor_b32_e32 v67, v67, v65
	v_lshlrev_b32_e32 v67, 4, v67
	v_lshl_or_b32 v173, v65, 8, v67
	v_add_u32_e32 v67, 8, v66
	v_xor_b32_e32 v67, v67, v65
	v_lshlrev_b32_e32 v67, 4, v67
	v_lshl_or_b32 v174, v65, 8, v67
	v_add_u32_e32 v67, 12, v66
	v_xor_b32_e32 v67, v67, v65
	v_lshlrev_b32_e32 v67, 4, v67
	v_lshl_or_b32 v175, v65, 8, v67
	v_bfe_u32 v68, v64, 2, 2
	v_and_b32_e32 v69, 3, v64
	v_lshl_add_u32 v70, v66, 2, v68
	v_and_b32_e32 v71, 7, v70
	v_lshlrev_b32_e32 v70, 8, v70
	v_lshl_add_u32 v70, v69, 3, v70
	v_add_u32_e32 v70, 0x10000, v70
	v_xor_b32_e32 v72, 0, v71
	v_lshl_add_u32 v176, v72, 5, v70
	v_xor_b32_e32 v72, 1, v71
	v_lshl_add_u32 v177, v72, 5, v70
	v_xor_b32_e32 v72, 2, v71
	v_lshl_add_u32 v178, v72, 5, v70
	v_xor_b32_e32 v72, 3, v71
	v_lshl_add_u32 v179, v72, 5, v70
	v_xor_b32_e32 v72, 4, v71
	v_lshl_add_u32 v180, v72, 5, v70
	v_xor_b32_e32 v72, 5, v71
	v_lshl_add_u32 v182, v72, 5, v70
	v_xor_b32_e32 v72, 6, v71
	v_lshl_add_u32 v216, v72, 5, v70
	v_xor_b32_e32 v72, 7, v71
	v_lshl_add_u32 v217, v72, 5, v70
	v_lshrrev_b32_e32 v72, 4, v218
	v_and_b32_e32 v74, 15, v218
	v_and_b32_e32 v73, 15, v72
	v_xor_b32_e32 v73, v73, v74
	v_mul_u32_u24_e32 v75, 0x5400, v72
	v_lshl_add_u32 v183, v73, 4, v75
	v_and_b32_e32 v73, 7, v72
	v_lshlrev_b32_e32 v73, 1, v73
	v_xor_b32_e32 v73, v73, v74
	v_lshl_add_u32 v181, v73, 4, v75
	v_add_u32_e32 v181, 0x200, v181
	v_readfirstlane_b32 s32, v218
	s_nop 3
	s_lshr_b32 s32, s32, 6
	s_lshl_b32 s32, s32, 10
	s_add_u32 s100, s98, 0xa8000
	s_addc_u32 s101, s99, 0
	s_sub_u32 s0, s98, 0x2a0000
	s_subb_u32 s1, s99, 0
	s_add_u32 s4, s0, 0xa8000
	s_addc_u32 s5, s1, 0
	s_add_i32 m0, s32, 0x10000
	s_nop 0
	global_load_lds_dwordx4 v181, s[0:1]
	s_add_i32 m0, s32, 0x12000
	s_nop 0
	global_load_lds_dwordx4 v181, s[4:5]
	s_add_u32 s0, s0, 0x150000
	s_addc_u32 s1, s1, 0
	s_add_u32 s4, s4, 0x150000
	s_addc_u32 s5, s5, 0
	s_add_i32 m0, s32, 0x14000
	s_nop 0
	global_load_lds_dwordx4 v181, s[0:1]
	s_add_i32 m0, s32, 0x16000
	s_nop 0
	global_load_lds_dwordx4 v181, s[4:5]
	s_add_u32 s0, s0, 0x150000
	s_addc_u32 s1, s1, 0
	s_add_u32 s4, s4, 0x150000
	s_addc_u32 s5, s5, 0
	s_add_i32 m0, s32, 0x8000
	s_nop 0
	global_load_lds_dwordx4 v183, s[98:99]
	s_add_i32 m0, s32, 0xa000
	s_nop 0
	global_load_lds_dwordx4 v183, s[100:101]
	s_add_u32 s98, s98, 0x150000
	s_addc_u32 s99, s99, 0
	s_add_u32 s100, s100, 0x150000
	s_addc_u32 s101, s101, 0
	s_add_i32 m0, s32, 0xc000
	s_nop 0
	global_load_lds_dwordx4 v183, s[98:99]
	s_add_i32 m0, s32, 0xe000
	s_nop 0
	global_load_lds_dwordx4 v183, s[100:101]
	s_add_u32 s98, s98, 0x150000
	s_addc_u32 s99, s99, 0
	s_add_u32 s100, s100, 0x150000
	s_addc_u32 s101, s101, 0
	v_and_b32_e32 v67, 1, v66
	v_lshl_add_u32 v67, v67, 5, v65
	v_lshlrev_b32_e32 v68, 2, v67
	v_add_u32_e32 v69, 64, v68
	s_mov_b32 vcc_lo, 0
	s_mov_b32 vcc_hi, -1
	ds_bpermute_b32 v200, v68, v124
	ds_bpermute_b32 v201, v68, v120
	ds_bpermute_b32 v202, v68, v125
	ds_bpermute_b32 v203, v68, v121
	ds_bpermute_b32 v204, v68, v126
	ds_bpermute_b32 v205, v68, v122
	ds_bpermute_b32 v206, v68, v127
	ds_bpermute_b32 v207, v68, v123
	ds_bpermute_b32 v208, v68, v116
	ds_bpermute_b32 v209, v68, v112
	ds_bpermute_b32 v210, v68, v117
	ds_bpermute_b32 v211, v68, v113
	ds_bpermute_b32 v212, v68, v118
	ds_bpermute_b32 v213, v68, v114
	s_waitcnt lgkmcnt(0)
	v_cndmask_b32_e64 v128, v200, v201, vcc
	v_cndmask_b32_e64 v129, v202, v203, vcc
	v_cndmask_b32_e64 v130, v204, v205, vcc
	v_cndmask_b32_e64 v131, v206, v207, vcc
	v_cndmask_b32_e64 v132, v208, v209, vcc
	v_cndmask_b32_e64 v133, v210, v211, vcc
	v_cndmask_b32_e64 v134, v212, v213, vcc
	ds_bpermute_b32 v200, v68, v119
	ds_bpermute_b32 v201, v68, v115
	ds_bpermute_b32 v202, v68, v108
	ds_bpermute_b32 v203, v68, v104
	ds_bpermute_b32 v204, v68, v109
	ds_bpermute_b32 v205, v68, v105
	ds_bpermute_b32 v206, v68, v110
	ds_bpermute_b32 v207, v68, v106
	ds_bpermute_b32 v208, v68, v111
	ds_bpermute_b32 v209, v68, v107
	ds_bpermute_b32 v210, v68, v100
	ds_bpermute_b32 v211, v68, v96
	ds_bpermute_b32 v212, v68, v101
	ds_bpermute_b32 v213, v68, v97
	s_waitcnt lgkmcnt(0)
	v_cndmask_b32_e64 v135, v200, v201, vcc
	v_cndmask_b32_e64 v136, v202, v203, vcc
	v_cndmask_b32_e64 v137, v204, v205, vcc
	v_cndmask_b32_e64 v138, v206, v207, vcc
	v_cndmask_b32_e64 v139, v208, v209, vcc
	v_cndmask_b32_e64 v140, v210, v211, vcc
	v_cndmask_b32_e64 v141, v212, v213, vcc
	ds_bpermute_b32 v200, v68, v102
	ds_bpermute_b32 v201, v68, v98
	ds_bpermute_b32 v202, v68, v103
	ds_bpermute_b32 v203, v68, v99
	ds_bpermute_b32 v204, v69, v124
	ds_bpermute_b32 v205, v69, v120
	ds_bpermute_b32 v206, v69, v125
	ds_bpermute_b32 v207, v69, v121
	ds_bpermute_b32 v208, v69, v126
	ds_bpermute_b32 v209, v69, v122
	ds_bpermute_b32 v210, v69, v127
	ds_bpermute_b32 v211, v69, v123
	ds_bpermute_b32 v212, v69, v116
	ds_bpermute_b32 v213, v69, v112
	s_waitcnt lgkmcnt(0)
	v_cndmask_b32_e64 v142, v200, v201, vcc
	v_cndmask_b32_e64 v143, v202, v203, vcc
	v_cndmask_b32_e64 v144, v204, v205, vcc
	v_cndmask_b32_e64 v145, v206, v207, vcc
	v_cndmask_b32_e64 v146, v208, v209, vcc
	v_cndmask_b32_e64 v147, v210, v211, vcc
	v_cndmask_b32_e64 v148, v212, v213, vcc
	ds_bpermute_b32 v200, v69, v117
	ds_bpermute_b32 v201, v69, v113
	ds_bpermute_b32 v202, v69, v118
	ds_bpermute_b32 v203, v69, v114
	ds_bpermute_b32 v204, v69, v119
	ds_bpermute_b32 v205, v69, v115
	ds_bpermute_b32 v206, v69, v108
	ds_bpermute_b32 v207, v69, v104
	ds_bpermute_b32 v208, v69, v109
	ds_bpermute_b32 v209, v69, v105
	ds_bpermute_b32 v210, v69, v110
	ds_bpermute_b32 v211, v69, v106
	ds_bpermute_b32 v212, v69, v111
	ds_bpermute_b32 v213, v69, v107
	s_waitcnt lgkmcnt(0)
; __device__ __forceinline__ void qkt(f32x16& p0, f32x16& p1, const bf16* Ks, const bf16x8* qr, int r32, int hi) {
;   p0 = f32x16{}; p1 = f32x16{};
; #pragma unroll
;   for (int d0 = 0; d0 < 8; ++d0) { int cb = (d0 * 16 + hi * 8) * 2;
;     bf16x8 b0 = *reinterpret_cast<const bf16x8*>((const char*)Ks + KSWZ(r32, cb));
;     bf16x8 b1 = *reinterpret_cast<const bf16x8*>((const char*)Ks + KSWZ(32 + r32, cb));
;     p0 = __builtin_amdgcn_mfma_f32_32x32x16_bf16(b0, qr[d0], p0, 0, 0, 0);
;     p1 = __builtin_amdgcn_mfma_f32_32x32x16_bf16(b1, qr[d0], p1, 0, 0, 0); }
; }
;     ...
;   PLOAD(0); asm volatile("s_waitcnt vmcnt(0)" ::: "memory"); PWRITE(0); __syncthreads();
;   qkt(pA0, pA1, KSUB(0, 0), qr, r32, hi); partialSM(pA0, pA1, m_reg, mnA, alA);
	v_cndmask_b32_e64 v149, v200, v201, vcc
	v_cndmask_b32_e64 v150, v202, v203, vcc
	v_cndmask_b32_e64 v151, v204, v205, vcc
	v_cndmask_b32_e64 v152, v206, v207, vcc
	v_cndmask_b32_e64 v153, v208, v209, vcc
	v_cndmask_b32_e64 v154, v210, v211, vcc
	v_cndmask_b32_e64 v155, v212, v213, vcc
	ds_bpermute_b32 v200, v69, v100
	ds_bpermute_b32 v201, v69, v96
	ds_bpermute_b32 v202, v69, v101
	ds_bpermute_b32 v203, v69, v97
	ds_bpermute_b32 v204, v69, v102
	ds_bpermute_b32 v205, v69, v98
	ds_bpermute_b32 v206, v69, v103
	ds_bpermute_b32 v207, v69, v99
	s_waitcnt lgkmcnt(0)
	v_cndmask_b32_e64 v156, v200, v201, vcc
	v_cndmask_b32_e64 v157, v202, v203, vcc
	v_cndmask_b32_e64 v158, v204, v205, vcc
	v_cndmask_b32_e64 v159, v206, v207, vcc
	v_mov_b32_e32 v96, v128
	v_mov_b32_e32 v97, v129
	v_mov_b32_e32 v98, v130
	v_mov_b32_e32 v99, v131
	v_mov_b32_e32 v100, v132
	v_mov_b32_e32 v101, v133
	v_mov_b32_e32 v102, v134
	v_mov_b32_e32 v103, v135
	v_mov_b32_e32 v104, v136
	v_mov_b32_e32 v105, v137
	v_mov_b32_e32 v106, v138
	v_mov_b32_e32 v107, v139
	v_mov_b32_e32 v108, v140
	v_mov_b32_e32 v109, v141
	v_mov_b32_e32 v110, v142
	v_mov_b32_e32 v111, v143
	v_mov_b32_e32 v112, v144
	v_mov_b32_e32 v113, v145
	v_mov_b32_e32 v114, v146
	v_mov_b32_e32 v115, v147
	v_mov_b32_e32 v116, v148
	v_mov_b32_e32 v117, v149
	v_mov_b32_e32 v118, v150
	v_mov_b32_e32 v119, v151
	v_mov_b32_e32 v120, v152
	v_mov_b32_e32 v121, v153
	v_mov_b32_e32 v122, v154
	v_mov_b32_e32 v123, v155
	v_mov_b32_e32 v124, v156
	v_mov_b32_e32 v125, v157
	v_mov_b32_e32 v126, v158
	v_mov_b32_e32 v127, v159
	v_mov_b32_e32 v169, 0
	v_mov_b32_e32 v222, 0
	s_mov_b32 s44, 0
	ds_read_b128 v[200:203], v172 offset:0
	ds_read_b128 v[204:207], v172 offset:4096
	ds_read_b128 v[208:211], v172 offset:8192
	ds_read_b128 v[212:215], v172 offset:12288
	ds_read_b128 v[230:233], v173 offset:0
	ds_read_b128 v[234:237], v173 offset:4096
	ds_read_b128 v[238:241], v173 offset:8192
	ds_read_b128 v[242:245], v173 offset:12288
	s_waitcnt lgkmcnt(7)
	v_mfma_f32_16x16x32_bf16 v[64:67], v[200:203], v[96:99], 0
	v_mfma_f32_16x16x32_bf16 v[68:71], v[200:203], v[112:115], 0
	ds_read_b128 v[200:203], v174 offset:0
	s_waitcnt lgkmcnt(7)
	v_mfma_f32_16x16x32_bf16 v[72:75], v[204:207], v[96:99], 0
	v_mfma_f32_16x16x32_bf16 v[76:79], v[204:207], v[112:115], 0
	ds_read_b128 v[204:207], v174 offset:4096
	s_waitcnt lgkmcnt(7)
	v_mfma_f32_16x16x32_bf16 v[80:83], v[208:211], v[96:99], 0
	v_mfma_f32_16x16x32_bf16 v[84:87], v[208:211], v[112:115], 0
	ds_read_b128 v[208:211], v174 offset:8192
	s_waitcnt lgkmcnt(7)
	v_mfma_f32_16x16x32_bf16 v[88:91], v[212:215], v[96:99], 0
	v_mfma_f32_16x16x32_bf16 v[92:95], v[212:215], v[112:115], 0
	ds_read_b128 v[212:215], v174 offset:12288
	s_waitcnt lgkmcnt(7)
	v_mfma_f32_16x16x32_bf16 v[64:67], v[230:233], v[100:103], v[64:67]
	v_mfma_f32_16x16x32_bf16 v[68:71], v[230:233], v[116:119], v[68:71]
	ds_read_b128 v[230:233], v175 offset:0
	s_waitcnt lgkmcnt(7)
	v_mfma_f32_16x16x32_bf16 v[72:75], v[234:237], v[100:103], v[72:75]
	v_mfma_f32_16x16x32_bf16 v[76:79], v[234:237], v[116:119], v[76:79]
	ds_read_b128 v[234:237], v175 offset:4096
	s_waitcnt lgkmcnt(7)
	v_mfma_f32_16x16x32_bf16 v[80:83], v[238:241], v[100:103], v[80:83]
	v_mfma_f32_16x16x32_bf16 v[84:87], v[238:241], v[116:119], v[84:87]
	ds_read_b128 v[238:241], v175 offset:8192
	s_waitcnt lgkmcnt(7)
	v_mfma_f32_16x16x32_bf16 v[88:91], v[242:245], v[100:103], v[88:91]
	v_mfma_f32_16x16x32_bf16 v[92:95], v[242:245], v[116:119], v[92:95]
	ds_read_b128 v[242:245], v175 offset:12288
	s_waitcnt lgkmcnt(7)
	v_mfma_f32_16x16x32_bf16 v[64:67], v[200:203], v[104:107], v[64:67]
	v_mfma_f32_16x16x32_bf16 v[68:71], v[200:203], v[120:123], v[68:71]
	s_waitcnt lgkmcnt(6)
	v_mfma_f32_16x16x32_bf16 v[72:75], v[204:207], v[104:107], v[72:75]
	v_mfma_f32_16x16x32_bf16 v[76:79], v[204:207], v[120:123], v[76:79]
	s_waitcnt lgkmcnt(5)
	v_mfma_f32_16x16x32_bf16 v[80:83], v[208:211], v[104:107], v[80:83]
	v_mfma_f32_16x16x32_bf16 v[84:87], v[208:211], v[120:123], v[84:87]
	s_waitcnt lgkmcnt(4)
	v_mfma_f32_16x16x32_bf16 v[88:91], v[212:215], v[104:107], v[88:91]
	v_mfma_f32_16x16x32_bf16 v[92:95], v[212:215], v[120:123], v[92:95]
	s_waitcnt lgkmcnt(3)
	v_mfma_f32_16x16x32_bf16 v[64:67], v[230:233], v[108:111], v[64:67]
	v_mfma_f32_16x16x32_bf16 v[68:71], v[230:233], v[124:127], v[68:71]
	s_waitcnt lgkmcnt(2)
	v_mfma_f32_16x16x32_bf16 v[72:75], v[234:237], v[108:111], v[72:75]
	v_mfma_f32_16x16x32_bf16 v[76:79], v[234:237], v[124:127], v[76:79]
	s_waitcnt lgkmcnt(1)
	v_mfma_f32_16x16x32_bf16 v[80:83], v[238:241], v[108:111], v[80:83]
	v_mfma_f32_16x16x32_bf16 v[84:87], v[238:241], v[124:127], v[84:87]
	s_waitcnt lgkmcnt(0)
	v_mfma_f32_16x16x32_bf16 v[88:91], v[242:245], v[108:111], v[88:91]
	v_mfma_f32_16x16x32_bf16 v[92:95], v[242:245], v[124:127], v[92:95]
	v_exp_f32_e32 v64, v64
	v_exp_f32_e32 v65, v65
	v_exp_f32_e32 v66, v66
	v_exp_f32_e32 v67, v67
	v_exp_f32_e32 v68, v68
	v_exp_f32_e32 v69, v69
	v_exp_f32_e32 v70, v70
	v_exp_f32_e32 v71, v71
	v_exp_f32_e32 v72, v72
	v_exp_f32_e32 v73, v73
	v_exp_f32_e32 v74, v74
	v_exp_f32_e32 v75, v75
	v_exp_f32_e32 v76, v76
	v_exp_f32_e32 v77, v77
	v_exp_f32_e32 v78, v78
	v_exp_f32_e32 v79, v79
	v_exp_f32_e32 v80, v80
	v_exp_f32_e32 v81, v81
	v_exp_f32_e32 v82, v82
	v_exp_f32_e32 v83, v83
	v_exp_f32_e32 v84, v84
	v_exp_f32_e32 v85, v85
	v_exp_f32_e32 v86, v86
	v_exp_f32_e32 v87, v87
	v_exp_f32_e32 v88, v88
	v_exp_f32_e32 v89, v89
	v_exp_f32_e32 v90, v90
	v_exp_f32_e32 v91, v91
	v_exp_f32_e32 v92, v92
	v_exp_f32_e32 v93, v93
	v_exp_f32_e32 v94, v94
	v_exp_f32_e32 v95, v95
	s_waitcnt vmcnt(0)
	ds_read_b128 v[200:203], v172 offset:16384
	ds_read_b128 v[204:207], v172 offset:20480
	ds_read_b128 v[208:211], v172 offset:24576
	ds_read_b128 v[212:215], v172 offset:28672
	ds_read_b128 v[230:233], v173 offset:16384
	ds_read_b128 v[234:237], v173 offset:20480
	ds_read_b128 v[238:241], v173 offset:24576
	ds_read_b128 v[242:245], v173 offset:28672
	s_barrier
	v_readfirstlane_b32 s44, v218
	s_nop 3
	s_cmp_ge_u32 s44, 0x100
	s_mov_b32 s44, 0
	s_cbranch_scc0 .Lprio_done
	s_setprio 1
.Lprio_done:
.Ldense_loop:
	s_waitcnt lgkmcnt(7)
	v_mfma_f32_16x16x32_bf16 v[128:131], v[200:203], v[96:99], 0
	v_add_f32_e32 v169, v169, v64
	s_add_i32 m0, s32, 0x0
	s_nop 0
	global_load_lds_dwordx4 v183, s[98:99]
	v_mfma_f32_16x16x32_bf16 v[132:135], v[200:203], v[112:115], 0
	ds_read_b128 v[200:203], v174 offset:16384
	v_add_f32_e32 v169, v169, v65
	v_cvt_pk_bf16_f32 v184, v64, v65
	s_waitcnt lgkmcnt(7)
	v_mfma_f32_16x16x32_bf16 v[136:139], v[204:207], v[96:99], 0
	v_add_f32_e32 v169, v169, v66
	v_mfma_f32_16x16x32_bf16 v[140:143], v[204:207], v[112:115], 0
	ds_read_b128 v[204:207], v174 offset:20480
	v_add_f32_e32 v169, v169, v67
	v_cvt_pk_bf16_f32 v185, v66, v67
	s_waitcnt lgkmcnt(7)
	v_mfma_f32_16x16x32_bf16 v[144:147], v[208:211], v[96:99], 0
	v_add_f32_e32 v222, v222, v68
	s_add_i32 m0, s32, 0x2000
	s_nop 0
	global_load_lds_dwordx4 v183, s[100:101]
	s_add_u32 s98, s98, 0x150000
	s_addc_u32 s99, s99, 0
	s_add_u32 s100, s100, 0x150000
	s_addc_u32 s101, s101, 0
	v_mfma_f32_16x16x32_bf16 v[148:151], v[208:211], v[112:115], 0
	ds_read_b128 v[208:211], v174 offset:24576
	v_add_f32_e32 v222, v222, v69
	v_cvt_pk_bf16_f32 v186, v72, v73
	s_waitcnt lgkmcnt(7)
	v_mfma_f32_16x16x32_bf16 v[152:155], v[212:215], v[96:99], 0
	v_add_f32_e32 v222, v222, v70
	v_mfma_f32_16x16x32_bf16 v[156:159], v[212:215], v[112:115], 0
	ds_read_b128 v[212:215], v174 offset:28672
	v_add_f32_e32 v222, v222, v71
	v_cvt_pk_bf16_f32 v187, v74, v75
	s_waitcnt lgkmcnt(7)
	v_mfma_f32_16x16x32_bf16 v[128:131], v[230:233], v[100:103], v[128:131]
	v_add_f32_e32 v169, v169, v72
	s_add_i32 m0, s32, 0x18000
	s_nop 0
	global_load_lds_dwordx4 v181, s[0:1]
	v_mfma_f32_16x16x32_bf16 v[132:135], v[230:233], v[116:119], v[132:135]
	ds_read_b128 v[230:233], v175 offset:16384
	v_add_f32_e32 v169, v169, v73
	v_cvt_pk_bf16_f32 v188, v80, v81
	s_waitcnt lgkmcnt(7)
	v_mfma_f32_16x16x32_bf16 v[136:139], v[234:237], v[100:103], v[136:139]
	v_add_f32_e32 v169, v169, v74
	v_mfma_f32_16x16x32_bf16 v[140:143], v[234:237], v[116:119], v[140:143]
	ds_read_b128 v[234:237], v175 offset:20480
	v_add_f32_e32 v169, v169, v75
	v_cvt_pk_bf16_f32 v189, v82, v83
	s_waitcnt lgkmcnt(7)
	v_mfma_f32_16x16x32_bf16 v[144:147], v[238:241], v[100:103], v[144:147]
	v_add_f32_e32 v222, v222, v76
	s_add_i32 m0, s32, 0x1a000
	s_nop 0
	global_load_lds_dwordx4 v181, s[4:5]
	s_add_u32 s0, s0, 0x150000
	s_addc_u32 s1, s1, 0
	s_add_u32 s4, s4, 0x150000
	s_addc_u32 s5, s5, 0
	v_mfma_f32_16x16x32_bf16 v[148:151], v[238:241], v[116:119], v[148:151]
	ds_read_b128 v[238:241], v175 offset:24576
	v_add_f32_e32 v222, v222, v77
	v_cvt_pk_bf16_f32 v190, v88, v89
	s_waitcnt lgkmcnt(7)
	v_mfma_f32_16x16x32_bf16 v[152:155], v[242:245], v[100:103], v[152:155]
	v_add_f32_e32 v222, v222, v78
	v_mfma_f32_16x16x32_bf16 v[156:159], v[242:245], v[116:119], v[156:159]
	ds_read_b128 v[242:245], v175 offset:28672
	v_add_f32_e32 v222, v222, v79
	v_cvt_pk_bf16_f32 v191, v90, v91
	s_waitcnt lgkmcnt(7)
	v_mfma_f32_16x16x32_bf16 v[128:131], v[200:203], v[104:107], v[128:131]
	v_add_f32_e32 v169, v169, v80
	v_mfma_f32_16x16x32_bf16 v[132:135], v[200:203], v[120:123], v[132:135]
	v_add_f32_e32 v169, v169, v81
	v_cvt_pk_bf16_f32 v192, v68, v69
	s_waitcnt lgkmcnt(6)
	v_mfma_f32_16x16x32_bf16 v[136:139], v[204:207], v[104:107], v[136:139]
	v_add_f32_e32 v169, v169, v82
	v_mfma_f32_16x16x32_bf16 v[140:143], v[204:207], v[120:123], v[140:143]
	v_add_f32_e32 v169, v169, v83
	v_cvt_pk_bf16_f32 v193, v70, v71
	s_waitcnt lgkmcnt(5)
	v_mfma_f32_16x16x32_bf16 v[144:147], v[208:211], v[104:107], v[144:147]
	v_add_f32_e32 v222, v222, v84
	v_mfma_f32_16x16x32_bf16 v[148:151], v[208:211], v[120:123], v[148:151]
	v_add_f32_e32 v222, v222, v85
	v_cvt_pk_bf16_f32 v194, v76, v77
	s_waitcnt lgkmcnt(4)
	v_mfma_f32_16x16x32_bf16 v[152:155], v[212:215], v[104:107], v[152:155]
	ds_read_b64_tr_b16 v[200:201], v176 offset:0
	ds_read_b64_tr_b16 v[202:203], v176 offset:4096
	v_add_f32_e32 v222, v222, v86
	v_mfma_f32_16x16x32_bf16 v[156:159], v[212:215], v[120:123], v[156:159]
	v_add_f32_e32 v222, v222, v87
	v_cvt_pk_bf16_f32 v195, v78, v79
	s_waitcnt lgkmcnt(5)
	v_mfma_f32_16x16x32_bf16 v[128:131], v[230:233], v[108:111], v[128:131]
	ds_read_b64_tr_b16 v[204:205], v177 offset:0
	ds_read_b64_tr_b16 v[206:207], v177 offset:4096
	v_add_f32_e32 v169, v169, v88
	v_mfma_f32_16x16x32_bf16 v[132:135], v[230:233], v[124:127], v[132:135]
	v_add_f32_e32 v169, v169, v89
	v_cvt_pk_bf16_f32 v196, v84, v85
	s_waitcnt lgkmcnt(6)
	v_mfma_f32_16x16x32_bf16 v[136:139], v[234:237], v[108:111], v[136:139]
	ds_read_b64_tr_b16 v[208:209], v178 offset:0
	ds_read_b64_tr_b16 v[210:211], v178 offset:4096
	v_add_f32_e32 v169, v169, v90
	v_mfma_f32_16x16x32_bf16 v[140:143], v[234:237], v[124:127], v[140:143]
	v_add_f32_e32 v169, v169, v91
	v_cvt_pk_bf16_f32 v197, v86, v87
	s_waitcnt lgkmcnt(7)
	v_mfma_f32_16x16x32_bf16 v[144:147], v[238:241], v[108:111], v[144:147]
	ds_read_b64_tr_b16 v[212:213], v179 offset:0
	ds_read_b64_tr_b16 v[214:215], v179 offset:4096
	v_add_f32_e32 v222, v222, v92
	v_mfma_f32_16x16x32_bf16 v[148:151], v[238:241], v[124:127], v[148:151]
	v_add_f32_e32 v222, v222, v93
	v_cvt_pk_bf16_f32 v198, v92, v93
	s_waitcnt lgkmcnt(8)
	v_mfma_f32_16x16x32_bf16 v[152:155], v[242:245], v[108:111], v[152:155]
	ds_read_b64_tr_b16 v[230:231], v180 offset:0
	ds_read_b64_tr_b16 v[232:233], v180 offset:4096
	v_add_f32_e32 v222, v222, v94
	v_mfma_f32_16x16x32_bf16 v[156:159], v[242:245], v[124:127], v[156:159]
	v_add_f32_e32 v222, v222, v95
	v_cvt_pk_bf16_f32 v199, v94, v95
	s_waitcnt lgkmcnt(8)
	v_mfma_f32_16x16x32_bf16 v[0:3], v[200:203], v[184:187], v[0:3]
	v_exp_f32_e32 v128, v128
	v_mfma_f32_16x16x32_bf16 v[32:35], v[200:203], v[192:195], v[32:35]
	ds_read_b64_tr_b16 v[234:235], v182 offset:0
	ds_read_b64_tr_b16 v[236:237], v182 offset:4096
	v_exp_f32_e32 v129, v129
	s_waitcnt lgkmcnt(8)
	v_mfma_f32_16x16x32_bf16 v[4:7], v[204:207], v[184:187], v[4:7]
	v_exp_f32_e32 v130, v130
	v_mfma_f32_16x16x32_bf16 v[36:39], v[204:207], v[192:195], v[36:39]
	ds_read_b64_tr_b16 v[238:239], v216 offset:0
	ds_read_b64_tr_b16 v[240:241], v216 offset:4096
	v_exp_f32_e32 v131, v131
	s_waitcnt lgkmcnt(8)
	v_mfma_f32_16x16x32_bf16 v[8:11], v[208:211], v[184:187], v[8:11]
	v_exp_f32_e32 v132, v132
	v_mfma_f32_16x16x32_bf16 v[40:43], v[208:211], v[192:195], v[40:43]
	ds_read_b64_tr_b16 v[242:243], v217 offset:0
	ds_read_b64_tr_b16 v[244:245], v217 offset:4096
	v_exp_f32_e32 v133, v133
	s_waitcnt lgkmcnt(8)
	v_mfma_f32_16x16x32_bf16 v[12:15], v[212:215], v[184:187], v[12:15]
	v_exp_f32_e32 v134, v134
	v_mfma_f32_16x16x32_bf16 v[44:47], v[212:215], v[192:195], v[44:47]
	ds_read_b64_tr_b16 v[200:201], v176 offset:8192
	ds_read_b64_tr_b16 v[202:203], v176 offset:12288
	v_exp_f32_e32 v135, v135
	s_waitcnt lgkmcnt(8)
	v_mfma_f32_16x16x32_bf16 v[16:19], v[230:233], v[184:187], v[16:19]
	v_exp_f32_e32 v136, v136
	v_mfma_f32_16x16x32_bf16 v[48:51], v[230:233], v[192:195], v[48:51]
	ds_read_b64_tr_b16 v[204:205], v177 offset:8192
	ds_read_b64_tr_b16 v[206:207], v177 offset:12288
	v_exp_f32_e32 v137, v137
	s_waitcnt lgkmcnt(8)
	v_mfma_f32_16x16x32_bf16 v[20:23], v[234:237], v[184:187], v[20:23]
	v_exp_f32_e32 v138, v138
	v_mfma_f32_16x16x32_bf16 v[52:55], v[234:237], v[192:195], v[52:55]
	ds_read_b64_tr_b16 v[208:209], v178 offset:8192
	ds_read_b64_tr_b16 v[210:211], v178 offset:12288
	v_exp_f32_e32 v139, v139
	s_waitcnt lgkmcnt(8)
	v_mfma_f32_16x16x32_bf16 v[24:27], v[238:241], v[184:187], v[24:27]
	v_exp_f32_e32 v140, v140
	v_mfma_f32_16x16x32_bf16 v[56:59], v[238:241], v[192:195], v[56:59]
	ds_read_b64_tr_b16 v[212:213], v179 offset:8192
	ds_read_b64_tr_b16 v[214:215], v179 offset:12288
	v_exp_f32_e32 v141, v141
	s_waitcnt lgkmcnt(8)
	v_mfma_f32_16x16x32_bf16 v[28:31], v[242:245], v[184:187], v[28:31]
	v_exp_f32_e32 v142, v142
	v_mfma_f32_16x16x32_bf16 v[60:63], v[242:245], v[192:195], v[60:63]
	ds_read_b64_tr_b16 v[230:231], v180 offset:8192
	ds_read_b64_tr_b16 v[232:233], v180 offset:12288
	v_exp_f32_e32 v143, v143
	s_waitcnt lgkmcnt(8)
	v_mfma_f32_16x16x32_bf16 v[0:3], v[200:203], v[188:191], v[0:3]
	v_exp_f32_e32 v144, v144
	v_mfma_f32_16x16x32_bf16 v[32:35], v[200:203], v[196:199], v[32:35]
	ds_read_b64_tr_b16 v[234:235], v182 offset:8192
	ds_read_b64_tr_b16 v[236:237], v182 offset:12288
	ds_read_b128 v[200:203], v172 offset:32768
	v_exp_f32_e32 v145, v145
	s_waitcnt lgkmcnt(9)
	v_mfma_f32_16x16x32_bf16 v[4:7], v[204:207], v[188:191], v[4:7]
	v_exp_f32_e32 v146, v146
	v_mfma_f32_16x16x32_bf16 v[36:39], v[204:207], v[196:199], v[36:39]
	ds_read_b64_tr_b16 v[238:239], v216 offset:8192
	ds_read_b64_tr_b16 v[240:241], v216 offset:12288
	ds_read_b128 v[204:207], v172 offset:36864
	v_exp_f32_e32 v147, v147
	s_waitcnt lgkmcnt(10)
	v_mfma_f32_16x16x32_bf16 v[8:11], v[208:211], v[188:191], v[8:11]
	v_exp_f32_e32 v148, v148
	v_mfma_f32_16x16x32_bf16 v[40:43], v[208:211], v[196:199], v[40:43]
	ds_read_b64_tr_b16 v[242:243], v217 offset:8192
	ds_read_b64_tr_b16 v[244:245], v217 offset:12288
	ds_read_b128 v[208:211], v172 offset:40960
	v_exp_f32_e32 v149, v149
	s_waitcnt lgkmcnt(11)
	v_mfma_f32_16x16x32_bf16 v[12:15], v[212:215], v[188:191], v[12:15]
	v_exp_f32_e32 v150, v150
	v_mfma_f32_16x16x32_bf16 v[44:47], v[212:215], v[196:199], v[44:47]
	ds_read_b128 v[212:215], v172 offset:45056
	v_exp_f32_e32 v151, v151
	s_waitcnt lgkmcnt(10)
	v_mfma_f32_16x16x32_bf16 v[16:19], v[230:233], v[188:191], v[16:19]
	v_exp_f32_e32 v152, v152
	v_mfma_f32_16x16x32_bf16 v[48:51], v[230:233], v[196:199], v[48:51]
	ds_read_b128 v[230:233], v173 offset:32768
	v_exp_f32_e32 v153, v153
	s_waitcnt lgkmcnt(9)
	v_mfma_f32_16x16x32_bf16 v[20:23], v[234:237], v[188:191], v[20:23]
	v_exp_f32_e32 v154, v154
	v_mfma_f32_16x16x32_bf16 v[52:55], v[234:237], v[196:199], v[52:55]
	ds_read_b128 v[234:237], v173 offset:36864
	v_exp_f32_e32 v155, v155
	s_waitcnt lgkmcnt(7)
	v_mfma_f32_16x16x32_bf16 v[24:27], v[238:241], v[188:191], v[24:27]
	v_exp_f32_e32 v156, v156
	v_mfma_f32_16x16x32_bf16 v[56:59], v[238:241], v[196:199], v[56:59]
	ds_read_b128 v[238:241], v173 offset:40960
	v_exp_f32_e32 v157, v157
	s_waitcnt lgkmcnt(5)
	v_mfma_f32_16x16x32_bf16 v[28:31], v[242:245], v[188:191], v[28:31]
	v_exp_f32_e32 v158, v158
	v_mfma_f32_16x16x32_bf16 v[60:63], v[242:245], v[196:199], v[60:63]
	ds_read_b128 v[242:245], v173 offset:45056
	v_exp_f32_e32 v159, v159
	s_waitcnt vmcnt(4)
	s_barrier
	v_mfma_f32_16x16x32_bf16 v[64:67], v[200:203], v[96:99], 0
	v_add_f32_e32 v169, v169, v128
	s_add_i32 m0, s32, 0x4000
	s_nop 0
	global_load_lds_dwordx4 v183, s[98:99]
	v_mfma_f32_16x16x32_bf16 v[68:71], v[200:203], v[112:115], 0
	ds_read_b128 v[200:203], v174 offset:32768
	v_add_f32_e32 v169, v169, v129
	v_cvt_pk_bf16_f32 v184, v128, v129
	v_mfma_f32_16x16x32_bf16 v[72:75], v[204:207], v[96:99], 0
	v_add_f32_e32 v169, v169, v130
	v_mfma_f32_16x16x32_bf16 v[76:79], v[204:207], v[112:115], 0
	ds_read_b128 v[204:207], v174 offset:36864
	v_add_f32_e32 v169, v169, v131
	v_cvt_pk_bf16_f32 v185, v130, v131
	s_waitcnt lgkmcnt(7)
	v_mfma_f32_16x16x32_bf16 v[80:83], v[208:211], v[96:99], 0
	v_add_f32_e32 v222, v222, v132
	s_add_i32 m0, s32, 0x6000
	s_nop 0
	global_load_lds_dwordx4 v183, s[100:101]
	s_add_u32 s98, s98, 0x150000
	s_addc_u32 s99, s99, 0
	s_add_u32 s100, s100, 0x150000
	s_addc_u32 s101, s101, 0
	v_mfma_f32_16x16x32_bf16 v[84:87], v[208:211], v[112:115], 0
	ds_read_b128 v[208:211], v174 offset:40960
	v_add_f32_e32 v222, v222, v133
	v_cvt_pk_bf16_f32 v186, v136, v137
	s_waitcnt lgkmcnt(7)
	v_mfma_f32_16x16x32_bf16 v[88:91], v[212:215], v[96:99], 0
	v_add_f32_e32 v222, v222, v134
	v_mfma_f32_16x16x32_bf16 v[92:95], v[212:215], v[112:115], 0
	ds_read_b128 v[212:215], v174 offset:45056
	v_add_f32_e32 v222, v222, v135
	v_cvt_pk_bf16_f32 v187, v138, v139
	s_waitcnt lgkmcnt(7)
	v_mfma_f32_16x16x32_bf16 v[64:67], v[230:233], v[100:103], v[64:67]
	v_add_f32_e32 v169, v169, v136
	s_add_i32 m0, s32, 0x1c000
	s_nop 0
	global_load_lds_dwordx4 v181, s[0:1]
	v_mfma_f32_16x16x32_bf16 v[68:71], v[230:233], v[116:119], v[68:71]
	ds_read_b128 v[230:233], v175 offset:32768
	v_add_f32_e32 v169, v169, v137
	v_cvt_pk_bf16_f32 v188, v144, v145
	s_waitcnt lgkmcnt(7)
	v_mfma_f32_16x16x32_bf16 v[72:75], v[234:237], v[100:103], v[72:75]
	v_add_f32_e32 v169, v169, v138
	v_mfma_f32_16x16x32_bf16 v[76:79], v[234:237], v[116:119], v[76:79]
	ds_read_b128 v[234:237], v175 offset:36864
	v_add_f32_e32 v169, v169, v139
	v_cvt_pk_bf16_f32 v189, v146, v147
	s_waitcnt lgkmcnt(7)
	v_mfma_f32_16x16x32_bf16 v[80:83], v[238:241], v[100:103], v[80:83]
	v_add_f32_e32 v222, v222, v140
	s_add_i32 m0, s32, 0x1e000
	s_nop 0
	global_load_lds_dwordx4 v181, s[4:5]
	s_add_u32 s0, s0, 0x150000
	s_addc_u32 s1, s1, 0
	s_add_u32 s4, s4, 0x150000
	s_addc_u32 s5, s5, 0
	v_mfma_f32_16x16x32_bf16 v[84:87], v[238:241], v[116:119], v[84:87]
	ds_read_b128 v[238:241], v175 offset:40960
	v_add_f32_e32 v222, v222, v141
	v_cvt_pk_bf16_f32 v190, v152, v153
	s_waitcnt lgkmcnt(7)
	v_mfma_f32_16x16x32_bf16 v[88:91], v[242:245], v[100:103], v[88:91]
	v_add_f32_e32 v222, v222, v142
	v_mfma_f32_16x16x32_bf16 v[92:95], v[242:245], v[116:119], v[92:95]
	ds_read_b128 v[242:245], v175 offset:45056
	v_add_f32_e32 v222, v222, v143
	v_cvt_pk_bf16_f32 v191, v154, v155
	s_waitcnt lgkmcnt(7)
	v_mfma_f32_16x16x32_bf16 v[64:67], v[200:203], v[104:107], v[64:67]
	v_add_f32_e32 v169, v169, v144
	v_mfma_f32_16x16x32_bf16 v[68:71], v[200:203], v[120:123], v[68:71]
	v_add_f32_e32 v169, v169, v145
	v_cvt_pk_bf16_f32 v192, v132, v133
	s_waitcnt lgkmcnt(6)
	v_mfma_f32_16x16x32_bf16 v[72:75], v[204:207], v[104:107], v[72:75]
	v_add_f32_e32 v169, v169, v146
	v_mfma_f32_16x16x32_bf16 v[76:79], v[204:207], v[120:123], v[76:79]
	v_add_f32_e32 v169, v169, v147
	v_cvt_pk_bf16_f32 v193, v134, v135
	s_waitcnt lgkmcnt(5)
	v_mfma_f32_16x16x32_bf16 v[80:83], v[208:211], v[104:107], v[80:83]
	v_add_f32_e32 v222, v222, v148
	v_mfma_f32_16x16x32_bf16 v[84:87], v[208:211], v[120:123], v[84:87]
	v_add_f32_e32 v222, v222, v149
	v_cvt_pk_bf16_f32 v194, v140, v141
	s_waitcnt lgkmcnt(4)
	v_mfma_f32_16x16x32_bf16 v[88:91], v[212:215], v[104:107], v[88:91]
	ds_read_b64_tr_b16 v[200:201], v176 offset:16384
	ds_read_b64_tr_b16 v[202:203], v176 offset:20480
	v_add_f32_e32 v222, v222, v150
	v_mfma_f32_16x16x32_bf16 v[92:95], v[212:215], v[120:123], v[92:95]
	v_add_f32_e32 v222, v222, v151
	v_cvt_pk_bf16_f32 v195, v142, v143
	s_waitcnt lgkmcnt(5)
	v_mfma_f32_16x16x32_bf16 v[64:67], v[230:233], v[108:111], v[64:67]
	ds_read_b64_tr_b16 v[204:205], v177 offset:16384
	ds_read_b64_tr_b16 v[206:207], v177 offset:20480
	v_add_f32_e32 v169, v169, v152
	v_mfma_f32_16x16x32_bf16 v[68:71], v[230:233], v[124:127], v[68:71]
	v_add_f32_e32 v169, v169, v153
	v_cvt_pk_bf16_f32 v196, v148, v149
	s_waitcnt lgkmcnt(6)
	v_mfma_f32_16x16x32_bf16 v[72:75], v[234:237], v[108:111], v[72:75]
	ds_read_b64_tr_b16 v[208:209], v178 offset:16384
	ds_read_b64_tr_b16 v[210:211], v178 offset:20480
	v_add_f32_e32 v169, v169, v154
	v_mfma_f32_16x16x32_bf16 v[76:79], v[234:237], v[124:127], v[76:79]
	v_add_f32_e32 v169, v169, v155
	v_cvt_pk_bf16_f32 v197, v150, v151
	s_waitcnt lgkmcnt(7)
	v_mfma_f32_16x16x32_bf16 v[80:83], v[238:241], v[108:111], v[80:83]
	ds_read_b64_tr_b16 v[212:213], v179 offset:16384
	ds_read_b64_tr_b16 v[214:215], v179 offset:20480
	v_add_f32_e32 v222, v222, v156
	v_mfma_f32_16x16x32_bf16 v[84:87], v[238:241], v[124:127], v[84:87]
	v_add_f32_e32 v222, v222, v157
	v_cvt_pk_bf16_f32 v198, v156, v157
	s_waitcnt lgkmcnt(8)
	v_mfma_f32_16x16x32_bf16 v[88:91], v[242:245], v[108:111], v[88:91]
	ds_read_b64_tr_b16 v[230:231], v180 offset:16384
	ds_read_b64_tr_b16 v[232:233], v180 offset:20480
	v_add_f32_e32 v222, v222, v158
	v_mfma_f32_16x16x32_bf16 v[92:95], v[242:245], v[124:127], v[92:95]
	v_add_f32_e32 v222, v222, v159
	v_cvt_pk_bf16_f32 v199, v158, v159
	s_waitcnt lgkmcnt(8)
	v_mfma_f32_16x16x32_bf16 v[0:3], v[200:203], v[184:187], v[0:3]
	v_exp_f32_e32 v64, v64
	v_mfma_f32_16x16x32_bf16 v[32:35], v[200:203], v[192:195], v[32:35]
	ds_read_b64_tr_b16 v[234:235], v182 offset:16384
	ds_read_b64_tr_b16 v[236:237], v182 offset:20480
	v_exp_f32_e32 v65, v65
	s_waitcnt lgkmcnt(8)
	v_mfma_f32_16x16x32_bf16 v[4:7], v[204:207], v[184:187], v[4:7]
	v_exp_f32_e32 v66, v66
	v_mfma_f32_16x16x32_bf16 v[36:39], v[204:207], v[192:195], v[36:39]
	ds_read_b64_tr_b16 v[238:239], v216 offset:16384
	ds_read_b64_tr_b16 v[240:241], v216 offset:20480
	v_exp_f32_e32 v67, v67
	s_waitcnt lgkmcnt(8)
	v_mfma_f32_16x16x32_bf16 v[8:11], v[208:211], v[184:187], v[8:11]
	v_exp_f32_e32 v68, v68
	v_mfma_f32_16x16x32_bf16 v[40:43], v[208:211], v[192:195], v[40:43]
	ds_read_b64_tr_b16 v[242:243], v217 offset:16384
	ds_read_b64_tr_b16 v[244:245], v217 offset:20480
	v_exp_f32_e32 v69, v69
	s_waitcnt lgkmcnt(8)
	v_mfma_f32_16x16x32_bf16 v[12:15], v[212:215], v[184:187], v[12:15]
	v_exp_f32_e32 v70, v70
	v_mfma_f32_16x16x32_bf16 v[44:47], v[212:215], v[192:195], v[44:47]
	ds_read_b64_tr_b16 v[200:201], v176 offset:24576
	ds_read_b64_tr_b16 v[202:203], v176 offset:28672
	v_exp_f32_e32 v71, v71
	s_waitcnt lgkmcnt(8)
	v_mfma_f32_16x16x32_bf16 v[16:19], v[230:233], v[184:187], v[16:19]
	v_exp_f32_e32 v72, v72
	v_mfma_f32_16x16x32_bf16 v[48:51], v[230:233], v[192:195], v[48:51]
	ds_read_b64_tr_b16 v[204:205], v177 offset:24576
	ds_read_b64_tr_b16 v[206:207], v177 offset:28672
	v_exp_f32_e32 v73, v73
	s_waitcnt lgkmcnt(8)
	v_mfma_f32_16x16x32_bf16 v[20:23], v[234:237], v[184:187], v[20:23]
	v_exp_f32_e32 v74, v74
	v_mfma_f32_16x16x32_bf16 v[52:55], v[234:237], v[192:195], v[52:55]
	ds_read_b64_tr_b16 v[208:209], v178 offset:24576
	ds_read_b64_tr_b16 v[210:211], v178 offset:28672
	v_exp_f32_e32 v75, v75
	s_waitcnt lgkmcnt(8)
	v_mfma_f32_16x16x32_bf16 v[24:27], v[238:241], v[184:187], v[24:27]
	v_exp_f32_e32 v76, v76
	v_mfma_f32_16x16x32_bf16 v[56:59], v[238:241], v[192:195], v[56:59]
	ds_read_b64_tr_b16 v[212:213], v179 offset:24576
	ds_read_b64_tr_b16 v[214:215], v179 offset:28672
	v_exp_f32_e32 v77, v77
	s_waitcnt lgkmcnt(8)
	v_mfma_f32_16x16x32_bf16 v[28:31], v[242:245], v[184:187], v[28:31]
	v_exp_f32_e32 v78, v78
	v_mfma_f32_16x16x32_bf16 v[60:63], v[242:245], v[192:195], v[60:63]
	ds_read_b64_tr_b16 v[230:231], v180 offset:24576
	ds_read_b64_tr_b16 v[232:233], v180 offset:28672
	v_exp_f32_e32 v79, v79
	s_waitcnt lgkmcnt(8)
	v_mfma_f32_16x16x32_bf16 v[0:3], v[200:203], v[188:191], v[0:3]
	v_exp_f32_e32 v80, v80
	v_mfma_f32_16x16x32_bf16 v[32:35], v[200:203], v[196:199], v[32:35]
	ds_read_b64_tr_b16 v[234:235], v182 offset:24576
	ds_read_b64_tr_b16 v[236:237], v182 offset:28672
	ds_read_b128 v[200:203], v172 offset:49152
	v_exp_f32_e32 v81, v81
	s_waitcnt lgkmcnt(9)
	v_mfma_f32_16x16x32_bf16 v[4:7], v[204:207], v[188:191], v[4:7]
	v_exp_f32_e32 v82, v82
	v_mfma_f32_16x16x32_bf16 v[36:39], v[204:207], v[196:199], v[36:39]
	ds_read_b64_tr_b16 v[238:239], v216 offset:24576
	ds_read_b64_tr_b16 v[240:241], v216 offset:28672
	ds_read_b128 v[204:207], v172 offset:53248
	v_exp_f32_e32 v83, v83
	s_waitcnt lgkmcnt(10)
	v_mfma_f32_16x16x32_bf16 v[8:11], v[208:211], v[188:191], v[8:11]
	v_exp_f32_e32 v84, v84
	v_mfma_f32_16x16x32_bf16 v[40:43], v[208:211], v[196:199], v[40:43]
	ds_read_b64_tr_b16 v[242:243], v217 offset:24576
	ds_read_b64_tr_b16 v[244:245], v217 offset:28672
	ds_read_b128 v[208:211], v172 offset:57344
	v_exp_f32_e32 v85, v85
	s_waitcnt lgkmcnt(11)
	v_mfma_f32_16x16x32_bf16 v[12:15], v[212:215], v[188:191], v[12:15]
	v_exp_f32_e32 v86, v86
	v_mfma_f32_16x16x32_bf16 v[44:47], v[212:215], v[196:199], v[44:47]
	ds_read_b128 v[212:215], v172 offset:61440
	v_exp_f32_e32 v87, v87
	s_waitcnt lgkmcnt(10)
	v_mfma_f32_16x16x32_bf16 v[16:19], v[230:233], v[188:191], v[16:19]
	v_exp_f32_e32 v88, v88
	v_mfma_f32_16x16x32_bf16 v[48:51], v[230:233], v[196:199], v[48:51]
	ds_read_b128 v[230:233], v173 offset:49152
	v_exp_f32_e32 v89, v89
	s_waitcnt lgkmcnt(9)
	v_mfma_f32_16x16x32_bf16 v[20:23], v[234:237], v[188:191], v[20:23]
	v_exp_f32_e32 v90, v90
	v_mfma_f32_16x16x32_bf16 v[52:55], v[234:237], v[196:199], v[52:55]
	ds_read_b128 v[234:237], v173 offset:53248
	v_exp_f32_e32 v91, v91
	s_waitcnt lgkmcnt(7)
	v_mfma_f32_16x16x32_bf16 v[24:27], v[238:241], v[188:191], v[24:27]
	v_exp_f32_e32 v92, v92
	v_mfma_f32_16x16x32_bf16 v[56:59], v[238:241], v[196:199], v[56:59]
	ds_read_b128 v[238:241], v173 offset:57344
	v_exp_f32_e32 v93, v93
	s_waitcnt lgkmcnt(5)
	v_mfma_f32_16x16x32_bf16 v[28:31], v[242:245], v[188:191], v[28:31]
	v_exp_f32_e32 v94, v94
	v_mfma_f32_16x16x32_bf16 v[60:63], v[242:245], v[196:199], v[60:63]
	ds_read_b128 v[242:245], v173 offset:61440
	v_exp_f32_e32 v95, v95
	s_waitcnt vmcnt(4)
	s_barrier
	v_mfma_f32_16x16x32_bf16 v[128:131], v[200:203], v[96:99], 0
	v_add_f32_e32 v169, v169, v64
	s_add_i32 m0, s32, 0x8000
	s_nop 0
	global_load_lds_dwordx4 v183, s[98:99]
	v_mfma_f32_16x16x32_bf16 v[132:135], v[200:203], v[112:115], 0
	ds_read_b128 v[200:203], v174 offset:49152
	v_add_f32_e32 v169, v169, v65
	v_cvt_pk_bf16_f32 v184, v64, v65
	v_mfma_f32_16x16x32_bf16 v[136:139], v[204:207], v[96:99], 0
	v_add_f32_e32 v169, v169, v66
	v_mfma_f32_16x16x32_bf16 v[140:143], v[204:207], v[112:115], 0
	ds_read_b128 v[204:207], v174 offset:53248
	v_add_f32_e32 v169, v169, v67
	v_cvt_pk_bf16_f32 v185, v66, v67
	s_waitcnt lgkmcnt(7)
	v_mfma_f32_16x16x32_bf16 v[144:147], v[208:211], v[96:99], 0
	v_add_f32_e32 v222, v222, v68
	s_add_i32 m0, s32, 0xa000
	s_nop 0
	global_load_lds_dwordx4 v183, s[100:101]
	s_add_u32 s98, s98, 0x150000
	s_addc_u32 s99, s99, 0
	s_add_u32 s100, s100, 0x150000
	s_addc_u32 s101, s101, 0
	v_mfma_f32_16x16x32_bf16 v[148:151], v[208:211], v[112:115], 0
	ds_read_b128 v[208:211], v174 offset:57344
	v_add_f32_e32 v222, v222, v69
	v_cvt_pk_bf16_f32 v186, v72, v73
	s_waitcnt lgkmcnt(7)
	v_mfma_f32_16x16x32_bf16 v[152:155], v[212:215], v[96:99], 0
	v_add_f32_e32 v222, v222, v70
	v_mfma_f32_16x16x32_bf16 v[156:159], v[212:215], v[112:115], 0
	ds_read_b128 v[212:215], v174 offset:61440
	v_add_f32_e32 v222, v222, v71
	v_cvt_pk_bf16_f32 v187, v74, v75
	s_waitcnt lgkmcnt(7)
	v_mfma_f32_16x16x32_bf16 v[128:131], v[230:233], v[100:103], v[128:131]
	v_add_f32_e32 v169, v169, v72
	s_add_i32 m0, s32, 0x10000
	s_nop 0
	global_load_lds_dwordx4 v181, s[0:1]
	v_mfma_f32_16x16x32_bf16 v[132:135], v[230:233], v[116:119], v[132:135]
	ds_read_b128 v[230:233], v175 offset:49152
	v_add_f32_e32 v169, v169, v73
	v_cvt_pk_bf16_f32 v188, v80, v81
	s_waitcnt lgkmcnt(7)
	v_mfma_f32_16x16x32_bf16 v[136:139], v[234:237], v[100:103], v[136:139]
	v_add_f32_e32 v169, v169, v74
	v_mfma_f32_16x16x32_bf16 v[140:143], v[234:237], v[116:119], v[140:143]
	ds_read_b128 v[234:237], v175 offset:53248
	v_add_f32_e32 v169, v169, v75
	v_cvt_pk_bf16_f32 v189, v82, v83
	s_waitcnt lgkmcnt(7)
	v_mfma_f32_16x16x32_bf16 v[144:147], v[238:241], v[100:103], v[144:147]
	v_add_f32_e32 v222, v222, v76
	s_add_i32 m0, s32, 0x12000
	s_nop 0
	global_load_lds_dwordx4 v181, s[4:5]
	s_add_u32 s0, s0, 0x150000
	s_addc_u32 s1, s1, 0
	s_add_u32 s4, s4, 0x150000
	s_addc_u32 s5, s5, 0
	v_mfma_f32_16x16x32_bf16 v[148:151], v[238:241], v[116:119], v[148:151]
	ds_read_b128 v[238:241], v175 offset:57344
	v_add_f32_e32 v222, v222, v77
	v_cvt_pk_bf16_f32 v190, v88, v89
	s_waitcnt lgkmcnt(7)
	v_mfma_f32_16x16x32_bf16 v[152:155], v[242:245], v[100:103], v[152:155]
	v_add_f32_e32 v222, v222, v78
	v_mfma_f32_16x16x32_bf16 v[156:159], v[242:245], v[116:119], v[156:159]
	ds_read_b128 v[242:245], v175 offset:61440
	v_add_f32_e32 v222, v222, v79
	v_cvt_pk_bf16_f32 v191, v90, v91
	s_waitcnt lgkmcnt(7)
	v_mfma_f32_16x16x32_bf16 v[128:131], v[200:203], v[104:107], v[128:131]
	v_add_f32_e32 v169, v169, v80
	v_mfma_f32_16x16x32_bf16 v[132:135], v[200:203], v[120:123], v[132:135]
	v_add_f32_e32 v169, v169, v81
	v_cvt_pk_bf16_f32 v192, v68, v69
	s_waitcnt lgkmcnt(6)
	v_mfma_f32_16x16x32_bf16 v[136:139], v[204:207], v[104:107], v[136:139]
	v_add_f32_e32 v169, v169, v82
	v_mfma_f32_16x16x32_bf16 v[140:143], v[204:207], v[120:123], v[140:143]
	v_add_f32_e32 v169, v169, v83
	v_cvt_pk_bf16_f32 v193, v70, v71
	s_waitcnt lgkmcnt(5)
	v_mfma_f32_16x16x32_bf16 v[144:147], v[208:211], v[104:107], v[144:147]
	v_add_f32_e32 v222, v222, v84
	v_mfma_f32_16x16x32_bf16 v[148:151], v[208:211], v[120:123], v[148:151]
	v_add_f32_e32 v222, v222, v85
	v_cvt_pk_bf16_f32 v194, v76, v77
	s_waitcnt lgkmcnt(4)
	v_mfma_f32_16x16x32_bf16 v[152:155], v[212:215], v[104:107], v[152:155]
	ds_read_b64_tr_b16 v[200:201], v176 offset:32768
	ds_read_b64_tr_b16 v[202:203], v176 offset:36864
	v_add_f32_e32 v222, v222, v86
	v_mfma_f32_16x16x32_bf16 v[156:159], v[212:215], v[120:123], v[156:159]
	v_add_f32_e32 v222, v222, v87
	v_cvt_pk_bf16_f32 v195, v78, v79
	s_waitcnt lgkmcnt(5)
	v_mfma_f32_16x16x32_bf16 v[128:131], v[230:233], v[108:111], v[128:131]
	ds_read_b64_tr_b16 v[204:205], v177 offset:32768
	ds_read_b64_tr_b16 v[206:207], v177 offset:36864
	v_add_f32_e32 v169, v169, v88
	v_mfma_f32_16x16x32_bf16 v[132:135], v[230:233], v[124:127], v[132:135]
	v_add_f32_e32 v169, v169, v89
	v_cvt_pk_bf16_f32 v196, v84, v85
	s_waitcnt lgkmcnt(6)
	v_mfma_f32_16x16x32_bf16 v[136:139], v[234:237], v[108:111], v[136:139]
	ds_read_b64_tr_b16 v[208:209], v178 offset:32768
	ds_read_b64_tr_b16 v[210:211], v178 offset:36864
	v_add_f32_e32 v169, v169, v90
	v_mfma_f32_16x16x32_bf16 v[140:143], v[234:237], v[124:127], v[140:143]
	v_add_f32_e32 v169, v169, v91
	v_cvt_pk_bf16_f32 v197, v86, v87
	s_waitcnt lgkmcnt(7)
	v_mfma_f32_16x16x32_bf16 v[144:147], v[238:241], v[108:111], v[144:147]
	ds_read_b64_tr_b16 v[212:213], v179 offset:32768
	ds_read_b64_tr_b16 v[214:215], v179 offset:36864
	v_add_f32_e32 v222, v222, v92
	v_mfma_f32_16x16x32_bf16 v[148:151], v[238:241], v[124:127], v[148:151]
	v_add_f32_e32 v222, v222, v93
	v_cvt_pk_bf16_f32 v198, v92, v93
	s_waitcnt lgkmcnt(8)
	v_mfma_f32_16x16x32_bf16 v[152:155], v[242:245], v[108:111], v[152:155]
	ds_read_b64_tr_b16 v[230:231], v180 offset:32768
	ds_read_b64_tr_b16 v[232:233], v180 offset:36864
	v_add_f32_e32 v222, v222, v94
	v_mfma_f32_16x16x32_bf16 v[156:159], v[242:245], v[124:127], v[156:159]
	v_add_f32_e32 v222, v222, v95
	v_cvt_pk_bf16_f32 v199, v94, v95
	s_waitcnt lgkmcnt(8)
	v_mfma_f32_16x16x32_bf16 v[0:3], v[200:203], v[184:187], v[0:3]
	v_exp_f32_e32 v128, v128
	v_mfma_f32_16x16x32_bf16 v[32:35], v[200:203], v[192:195], v[32:35]
	ds_read_b64_tr_b16 v[234:235], v182 offset:32768
	ds_read_b64_tr_b16 v[236:237], v182 offset:36864
	v_exp_f32_e32 v129, v129
	s_waitcnt lgkmcnt(8)
	v_mfma_f32_16x16x32_bf16 v[4:7], v[204:207], v[184:187], v[4:7]
	v_exp_f32_e32 v130, v130
	v_mfma_f32_16x16x32_bf16 v[36:39], v[204:207], v[192:195], v[36:39]
	ds_read_b64_tr_b16 v[238:239], v216 offset:32768
	ds_read_b64_tr_b16 v[240:241], v216 offset:36864
	v_exp_f32_e32 v131, v131
	s_waitcnt lgkmcnt(8)
	v_mfma_f32_16x16x32_bf16 v[8:11], v[208:211], v[184:187], v[8:11]
	v_exp_f32_e32 v132, v132
	v_mfma_f32_16x16x32_bf16 v[40:43], v[208:211], v[192:195], v[40:43]
	ds_read_b64_tr_b16 v[242:243], v217 offset:32768
	ds_read_b64_tr_b16 v[244:245], v217 offset:36864
	v_exp_f32_e32 v133, v133
	s_waitcnt lgkmcnt(8)
	v_mfma_f32_16x16x32_bf16 v[12:15], v[212:215], v[184:187], v[12:15]
	v_exp_f32_e32 v134, v134
	v_mfma_f32_16x16x32_bf16 v[44:47], v[212:215], v[192:195], v[44:47]
	ds_read_b64_tr_b16 v[200:201], v176 offset:40960
	ds_read_b64_tr_b16 v[202:203], v176 offset:45056
	v_exp_f32_e32 v135, v135
	s_waitcnt lgkmcnt(8)
	v_mfma_f32_16x16x32_bf16 v[16:19], v[230:233], v[184:187], v[16:19]
	v_exp_f32_e32 v136, v136
	v_mfma_f32_16x16x32_bf16 v[48:51], v[230:233], v[192:195], v[48:51]
	ds_read_b64_tr_b16 v[204:205], v177 offset:40960
	ds_read_b64_tr_b16 v[206:207], v177 offset:45056
	v_exp_f32_e32 v137, v137
	s_waitcnt lgkmcnt(8)
	v_mfma_f32_16x16x32_bf16 v[20:23], v[234:237], v[184:187], v[20:23]
	v_exp_f32_e32 v138, v138
	v_mfma_f32_16x16x32_bf16 v[52:55], v[234:237], v[192:195], v[52:55]
	ds_read_b64_tr_b16 v[208:209], v178 offset:40960
	ds_read_b64_tr_b16 v[210:211], v178 offset:45056
	v_exp_f32_e32 v139, v139
	s_waitcnt lgkmcnt(8)
	v_mfma_f32_16x16x32_bf16 v[24:27], v[238:241], v[184:187], v[24:27]
	v_exp_f32_e32 v140, v140
	v_mfma_f32_16x16x32_bf16 v[56:59], v[238:241], v[192:195], v[56:59]
	ds_read_b64_tr_b16 v[212:213], v179 offset:40960
	ds_read_b64_tr_b16 v[214:215], v179 offset:45056
	v_exp_f32_e32 v141, v141
	s_waitcnt lgkmcnt(8)
	v_mfma_f32_16x16x32_bf16 v[28:31], v[242:245], v[184:187], v[28:31]
	v_exp_f32_e32 v142, v142
	v_mfma_f32_16x16x32_bf16 v[60:63], v[242:245], v[192:195], v[60:63]
	ds_read_b64_tr_b16 v[230:231], v180 offset:40960
	ds_read_b64_tr_b16 v[232:233], v180 offset:45056
	v_exp_f32_e32 v143, v143
	s_waitcnt lgkmcnt(8)
	v_mfma_f32_16x16x32_bf16 v[0:3], v[200:203], v[188:191], v[0:3]
	v_exp_f32_e32 v144, v144
	v_mfma_f32_16x16x32_bf16 v[32:35], v[200:203], v[196:199], v[32:35]
	ds_read_b64_tr_b16 v[234:235], v182 offset:40960
	ds_read_b64_tr_b16 v[236:237], v182 offset:45056
	ds_read_b128 v[200:203], v172 offset:0
	v_exp_f32_e32 v145, v145
	s_waitcnt lgkmcnt(9)
	v_mfma_f32_16x16x32_bf16 v[4:7], v[204:207], v[188:191], v[4:7]
	v_exp_f32_e32 v146, v146
	v_mfma_f32_16x16x32_bf16 v[36:39], v[204:207], v[196:199], v[36:39]
	ds_read_b64_tr_b16 v[238:239], v216 offset:40960
	ds_read_b64_tr_b16 v[240:241], v216 offset:45056
	ds_read_b128 v[204:207], v172 offset:4096
	v_exp_f32_e32 v147, v147
	s_waitcnt lgkmcnt(10)
	v_mfma_f32_16x16x32_bf16 v[8:11], v[208:211], v[188:191], v[8:11]
	v_exp_f32_e32 v148, v148
	v_mfma_f32_16x16x32_bf16 v[40:43], v[208:211], v[196:199], v[40:43]
	ds_read_b64_tr_b16 v[242:243], v217 offset:40960
	ds_read_b64_tr_b16 v[244:245], v217 offset:45056
	ds_read_b128 v[208:211], v172 offset:8192
	v_exp_f32_e32 v149, v149
	s_waitcnt lgkmcnt(11)
	v_mfma_f32_16x16x32_bf16 v[12:15], v[212:215], v[188:191], v[12:15]
	v_exp_f32_e32 v150, v150
	v_mfma_f32_16x16x32_bf16 v[44:47], v[212:215], v[196:199], v[44:47]
	ds_read_b128 v[212:215], v172 offset:12288
	v_exp_f32_e32 v151, v151
	s_waitcnt lgkmcnt(10)
	v_mfma_f32_16x16x32_bf16 v[16:19], v[230:233], v[188:191], v[16:19]
	v_exp_f32_e32 v152, v152
	v_mfma_f32_16x16x32_bf16 v[48:51], v[230:233], v[196:199], v[48:51]
	ds_read_b128 v[230:233], v173 offset:0
	v_exp_f32_e32 v153, v153
	s_waitcnt lgkmcnt(9)
	v_mfma_f32_16x16x32_bf16 v[20:23], v[234:237], v[188:191], v[20:23]
	v_exp_f32_e32 v154, v154
	v_mfma_f32_16x16x32_bf16 v[52:55], v[234:237], v[196:199], v[52:55]
	ds_read_b128 v[234:237], v173 offset:4096
	v_exp_f32_e32 v155, v155
	s_waitcnt lgkmcnt(7)
	v_mfma_f32_16x16x32_bf16 v[24:27], v[238:241], v[188:191], v[24:27]
	v_exp_f32_e32 v156, v156
	v_mfma_f32_16x16x32_bf16 v[56:59], v[238:241], v[196:199], v[56:59]
	ds_read_b128 v[238:241], v173 offset:8192
	v_exp_f32_e32 v157, v157
	s_waitcnt lgkmcnt(5)
	v_mfma_f32_16x16x32_bf16 v[28:31], v[242:245], v[188:191], v[28:31]
	v_exp_f32_e32 v158, v158
	v_mfma_f32_16x16x32_bf16 v[60:63], v[242:245], v[196:199], v[60:63]
	ds_read_b128 v[242:245], v173 offset:12288
	v_exp_f32_e32 v159, v159
	s_waitcnt vmcnt(4)
	s_barrier
	v_mfma_f32_16x16x32_bf16 v[64:67], v[200:203], v[96:99], 0
	v_add_f32_e32 v169, v169, v128
	s_add_i32 m0, s32, 0xc000
	s_nop 0
	global_load_lds_dwordx4 v183, s[98:99]
	v_mfma_f32_16x16x32_bf16 v[68:71], v[200:203], v[112:115], 0
	ds_read_b128 v[200:203], v174 offset:0
	v_add_f32_e32 v169, v169, v129
	v_cvt_pk_bf16_f32 v184, v128, v129
	v_mfma_f32_16x16x32_bf16 v[72:75], v[204:207], v[96:99], 0
	v_add_f32_e32 v169, v169, v130
	v_mfma_f32_16x16x32_bf16 v[76:79], v[204:207], v[112:115], 0
	ds_read_b128 v[204:207], v174 offset:4096
	v_add_f32_e32 v169, v169, v131
	v_cvt_pk_bf16_f32 v185, v130, v131
	s_waitcnt lgkmcnt(7)
	v_mfma_f32_16x16x32_bf16 v[80:83], v[208:211], v[96:99], 0
	v_add_f32_e32 v222, v222, v132
	s_add_i32 m0, s32, 0xe000
	s_nop 0
	global_load_lds_dwordx4 v183, s[100:101]
	s_add_u32 s98, s98, 0x150000
	s_addc_u32 s99, s99, 0
	s_add_u32 s100, s100, 0x150000
	s_addc_u32 s101, s101, 0
	v_mfma_f32_16x16x32_bf16 v[84:87], v[208:211], v[112:115], 0
	ds_read_b128 v[208:211], v174 offset:8192
	v_add_f32_e32 v222, v222, v133
	v_cvt_pk_bf16_f32 v186, v136, v137
	s_waitcnt lgkmcnt(7)
	v_mfma_f32_16x16x32_bf16 v[88:91], v[212:215], v[96:99], 0
	v_add_f32_e32 v222, v222, v134
	v_mfma_f32_16x16x32_bf16 v[92:95], v[212:215], v[112:115], 0
	ds_read_b128 v[212:215], v174 offset:12288
	v_add_f32_e32 v222, v222, v135
	v_cvt_pk_bf16_f32 v187, v138, v139
	s_waitcnt lgkmcnt(7)
	v_mfma_f32_16x16x32_bf16 v[64:67], v[230:233], v[100:103], v[64:67]
	v_add_f32_e32 v169, v169, v136
	s_add_i32 m0, s32, 0x14000
	s_nop 0
	global_load_lds_dwordx4 v181, s[0:1]
	v_mfma_f32_16x16x32_bf16 v[68:71], v[230:233], v[116:119], v[68:71]
	ds_read_b128 v[230:233], v175 offset:0
	v_add_f32_e32 v169, v169, v137
	v_cvt_pk_bf16_f32 v188, v144, v145
	s_waitcnt lgkmcnt(7)
	v_mfma_f32_16x16x32_bf16 v[72:75], v[234:237], v[100:103], v[72:75]
	v_add_f32_e32 v169, v169, v138
	v_mfma_f32_16x16x32_bf16 v[76:79], v[234:237], v[116:119], v[76:79]
	ds_read_b128 v[234:237], v175 offset:4096
	v_add_f32_e32 v169, v169, v139
	v_cvt_pk_bf16_f32 v189, v146, v147
	s_waitcnt lgkmcnt(7)
	v_mfma_f32_16x16x32_bf16 v[80:83], v[238:241], v[100:103], v[80:83]
	v_add_f32_e32 v222, v222, v140
	s_add_i32 m0, s32, 0x16000
	s_nop 0
	global_load_lds_dwordx4 v181, s[4:5]
	s_add_u32 s0, s0, 0x150000
	s_addc_u32 s1, s1, 0
	s_add_u32 s4, s4, 0x150000
	s_addc_u32 s5, s5, 0
	v_mfma_f32_16x16x32_bf16 v[84:87], v[238:241], v[116:119], v[84:87]
	ds_read_b128 v[238:241], v175 offset:8192
	v_add_f32_e32 v222, v222, v141
	v_cvt_pk_bf16_f32 v190, v152, v153
	s_waitcnt lgkmcnt(7)
	v_mfma_f32_16x16x32_bf16 v[88:91], v[242:245], v[100:103], v[88:91]
	v_add_f32_e32 v222, v222, v142
	v_mfma_f32_16x16x32_bf16 v[92:95], v[242:245], v[116:119], v[92:95]
	ds_read_b128 v[242:245], v175 offset:12288
	v_add_f32_e32 v222, v222, v143
	v_cvt_pk_bf16_f32 v191, v154, v155
	s_waitcnt lgkmcnt(7)
	v_mfma_f32_16x16x32_bf16 v[64:67], v[200:203], v[104:107], v[64:67]
	v_add_f32_e32 v169, v169, v144
	v_mfma_f32_16x16x32_bf16 v[68:71], v[200:203], v[120:123], v[68:71]
	v_add_f32_e32 v169, v169, v145
	v_cvt_pk_bf16_f32 v192, v132, v133
	s_waitcnt lgkmcnt(6)
	v_mfma_f32_16x16x32_bf16 v[72:75], v[204:207], v[104:107], v[72:75]
	v_add_f32_e32 v169, v169, v146
	v_mfma_f32_16x16x32_bf16 v[76:79], v[204:207], v[120:123], v[76:79]
	v_add_f32_e32 v169, v169, v147
	v_cvt_pk_bf16_f32 v193, v134, v135
	s_waitcnt lgkmcnt(5)
	v_mfma_f32_16x16x32_bf16 v[80:83], v[208:211], v[104:107], v[80:83]
	v_add_f32_e32 v222, v222, v148
	v_mfma_f32_16x16x32_bf16 v[84:87], v[208:211], v[120:123], v[84:87]
	v_add_f32_e32 v222, v222, v149
	v_cvt_pk_bf16_f32 v194, v140, v141
	s_waitcnt lgkmcnt(4)
	v_mfma_f32_16x16x32_bf16 v[88:91], v[212:215], v[104:107], v[88:91]
	ds_read_b64_tr_b16 v[200:201], v176 offset:49152
	ds_read_b64_tr_b16 v[202:203], v176 offset:53248
	v_add_f32_e32 v222, v222, v150
	v_mfma_f32_16x16x32_bf16 v[92:95], v[212:215], v[120:123], v[92:95]
	v_add_f32_e32 v222, v222, v151
	v_cvt_pk_bf16_f32 v195, v142, v143
	s_waitcnt lgkmcnt(5)
	v_mfma_f32_16x16x32_bf16 v[64:67], v[230:233], v[108:111], v[64:67]
	ds_read_b64_tr_b16 v[204:205], v177 offset:49152
	ds_read_b64_tr_b16 v[206:207], v177 offset:53248
	v_add_f32_e32 v169, v169, v152
	v_mfma_f32_16x16x32_bf16 v[68:71], v[230:233], v[124:127], v[68:71]
	v_add_f32_e32 v169, v169, v153
	v_cvt_pk_bf16_f32 v196, v148, v149
	s_waitcnt lgkmcnt(6)
	v_mfma_f32_16x16x32_bf16 v[72:75], v[234:237], v[108:111], v[72:75]
	ds_read_b64_tr_b16 v[208:209], v178 offset:49152
	ds_read_b64_tr_b16 v[210:211], v178 offset:53248
	v_add_f32_e32 v169, v169, v154
	v_mfma_f32_16x16x32_bf16 v[76:79], v[234:237], v[124:127], v[76:79]
	v_add_f32_e32 v169, v169, v155
	v_cvt_pk_bf16_f32 v197, v150, v151
	s_waitcnt lgkmcnt(7)
	v_mfma_f32_16x16x32_bf16 v[80:83], v[238:241], v[108:111], v[80:83]
	ds_read_b64_tr_b16 v[212:213], v179 offset:49152
	ds_read_b64_tr_b16 v[214:215], v179 offset:53248
	v_add_f32_e32 v222, v222, v156
	v_mfma_f32_16x16x32_bf16 v[84:87], v[238:241], v[124:127], v[84:87]
	v_add_f32_e32 v222, v222, v157
	v_cvt_pk_bf16_f32 v198, v156, v157
	s_waitcnt lgkmcnt(8)
	v_mfma_f32_16x16x32_bf16 v[88:91], v[242:245], v[108:111], v[88:91]
	ds_read_b64_tr_b16 v[230:231], v180 offset:49152
	ds_read_b64_tr_b16 v[232:233], v180 offset:53248
	v_add_f32_e32 v222, v222, v158
	v_mfma_f32_16x16x32_bf16 v[92:95], v[242:245], v[124:127], v[92:95]
	v_add_f32_e32 v222, v222, v159
	v_cvt_pk_bf16_f32 v199, v158, v159
	s_waitcnt lgkmcnt(8)
	v_mfma_f32_16x16x32_bf16 v[0:3], v[200:203], v[184:187], v[0:3]
	v_exp_f32_e32 v64, v64
	v_mfma_f32_16x16x32_bf16 v[32:35], v[200:203], v[192:195], v[32:35]
	ds_read_b64_tr_b16 v[234:235], v182 offset:49152
	ds_read_b64_tr_b16 v[236:237], v182 offset:53248
	v_exp_f32_e32 v65, v65
	s_waitcnt lgkmcnt(8)
;     ...
;   for (int p = 0; p + 2 < NP; p += 2) {
;     PAIR_FULL(0, 1, p + 1);
;     PAIR_FULL(1, 0, p + 2);
;   }
	v_mfma_f32_16x16x32_bf16 v[4:7], v[204:207], v[184:187], v[4:7]
	v_exp_f32_e32 v66, v66
	v_mfma_f32_16x16x32_bf16 v[36:39], v[204:207], v[192:195], v[36:39]
	ds_read_b64_tr_b16 v[238:239], v216 offset:49152
	ds_read_b64_tr_b16 v[240:241], v216 offset:53248
	v_exp_f32_e32 v67, v67
	s_waitcnt lgkmcnt(8)
	v_mfma_f32_16x16x32_bf16 v[8:11], v[208:211], v[184:187], v[8:11]
	v_exp_f32_e32 v68, v68
	v_mfma_f32_16x16x32_bf16 v[40:43], v[208:211], v[192:195], v[40:43]
	ds_read_b64_tr_b16 v[242:243], v217 offset:49152
	ds_read_b64_tr_b16 v[244:245], v217 offset:53248
	v_exp_f32_e32 v69, v69
	s_waitcnt lgkmcnt(8)
	v_mfma_f32_16x16x32_bf16 v[12:15], v[212:215], v[184:187], v[12:15]
	v_exp_f32_e32 v70, v70
	v_mfma_f32_16x16x32_bf16 v[44:47], v[212:215], v[192:195], v[44:47]
	ds_read_b64_tr_b16 v[200:201], v176 offset:57344
	ds_read_b64_tr_b16 v[202:203], v176 offset:61440
	v_exp_f32_e32 v71, v71
	s_waitcnt lgkmcnt(8)
	v_mfma_f32_16x16x32_bf16 v[16:19], v[230:233], v[184:187], v[16:19]
	v_exp_f32_e32 v72, v72
	v_mfma_f32_16x16x32_bf16 v[48:51], v[230:233], v[192:195], v[48:51]
	ds_read_b64_tr_b16 v[204:205], v177 offset:57344
	ds_read_b64_tr_b16 v[206:207], v177 offset:61440
	v_exp_f32_e32 v73, v73
	s_waitcnt lgkmcnt(8)
	v_mfma_f32_16x16x32_bf16 v[20:23], v[234:237], v[184:187], v[20:23]
	v_exp_f32_e32 v74, v74
	v_mfma_f32_16x16x32_bf16 v[52:55], v[234:237], v[192:195], v[52:55]
	ds_read_b64_tr_b16 v[208:209], v178 offset:57344
	ds_read_b64_tr_b16 v[210:211], v178 offset:61440
	v_exp_f32_e32 v75, v75
	s_waitcnt lgkmcnt(8)
	v_mfma_f32_16x16x32_bf16 v[24:27], v[238:241], v[184:187], v[24:27]
	v_exp_f32_e32 v76, v76
	v_mfma_f32_16x16x32_bf16 v[56:59], v[238:241], v[192:195], v[56:59]
	ds_read_b64_tr_b16 v[212:213], v179 offset:57344
	ds_read_b64_tr_b16 v[214:215], v179 offset:61440
	v_exp_f32_e32 v77, v77
	s_waitcnt lgkmcnt(8)
	v_mfma_f32_16x16x32_bf16 v[28:31], v[242:245], v[184:187], v[28:31]
	v_exp_f32_e32 v78, v78
	v_mfma_f32_16x16x32_bf16 v[60:63], v[242:245], v[192:195], v[60:63]
	ds_read_b64_tr_b16 v[230:231], v180 offset:57344
	ds_read_b64_tr_b16 v[232:233], v180 offset:61440
	v_exp_f32_e32 v79, v79
	s_waitcnt lgkmcnt(8)
	v_mfma_f32_16x16x32_bf16 v[0:3], v[200:203], v[188:191], v[0:3]
	v_exp_f32_e32 v80, v80
	v_mfma_f32_16x16x32_bf16 v[32:35], v[200:203], v[196:199], v[32:35]
	ds_read_b64_tr_b16 v[234:235], v182 offset:57344
	ds_read_b64_tr_b16 v[236:237], v182 offset:61440
	ds_read_b128 v[200:203], v172 offset:16384
	v_exp_f32_e32 v81, v81
	s_waitcnt lgkmcnt(9)
	v_mfma_f32_16x16x32_bf16 v[4:7], v[204:207], v[188:191], v[4:7]
	v_exp_f32_e32 v82, v82
	v_mfma_f32_16x16x32_bf16 v[36:39], v[204:207], v[196:199], v[36:39]
	ds_read_b64_tr_b16 v[238:239], v216 offset:57344
	ds_read_b64_tr_b16 v[240:241], v216 offset:61440
	ds_read_b128 v[204:207], v172 offset:20480
	v_exp_f32_e32 v83, v83
	s_waitcnt lgkmcnt(10)
	v_mfma_f32_16x16x32_bf16 v[8:11], v[208:211], v[188:191], v[8:11]
	v_exp_f32_e32 v84, v84
	v_mfma_f32_16x16x32_bf16 v[40:43], v[208:211], v[196:199], v[40:43]
	ds_read_b64_tr_b16 v[242:243], v217 offset:57344
	ds_read_b64_tr_b16 v[244:245], v217 offset:61440
	ds_read_b128 v[208:211], v172 offset:24576
	v_exp_f32_e32 v85, v85
	s_waitcnt lgkmcnt(11)
	v_mfma_f32_16x16x32_bf16 v[12:15], v[212:215], v[188:191], v[12:15]
	v_exp_f32_e32 v86, v86
	v_mfma_f32_16x16x32_bf16 v[44:47], v[212:215], v[196:199], v[44:47]
	ds_read_b128 v[212:215], v172 offset:28672
	v_exp_f32_e32 v87, v87
	s_waitcnt lgkmcnt(10)
	v_mfma_f32_16x16x32_bf16 v[16:19], v[230:233], v[188:191], v[16:19]
	v_exp_f32_e32 v88, v88
	v_mfma_f32_16x16x32_bf16 v[48:51], v[230:233], v[196:199], v[48:51]
	ds_read_b128 v[230:233], v173 offset:16384
	v_exp_f32_e32 v89, v89
	s_waitcnt lgkmcnt(9)
	v_mfma_f32_16x16x32_bf16 v[20:23], v[234:237], v[188:191], v[20:23]
	v_exp_f32_e32 v90, v90
	v_mfma_f32_16x16x32_bf16 v[52:55], v[234:237], v[196:199], v[52:55]
	ds_read_b128 v[234:237], v173 offset:20480
	v_exp_f32_e32 v91, v91
	s_waitcnt lgkmcnt(7)
	v_mfma_f32_16x16x32_bf16 v[24:27], v[238:241], v[188:191], v[24:27]
	v_exp_f32_e32 v92, v92
	v_mfma_f32_16x16x32_bf16 v[56:59], v[238:241], v[196:199], v[56:59]
	ds_read_b128 v[238:241], v173 offset:24576
	v_exp_f32_e32 v93, v93
	s_waitcnt lgkmcnt(5)
	v_mfma_f32_16x16x32_bf16 v[28:31], v[242:245], v[188:191], v[28:31]
	v_exp_f32_e32 v94, v94
	v_mfma_f32_16x16x32_bf16 v[60:63], v[242:245], v[196:199], v[60:63]
	ds_read_b128 v[242:245], v173 offset:28672
	v_exp_f32_e32 v95, v95
	s_waitcnt vmcnt(4)
	s_barrier
	s_add_i32 s44, s44, 1
	s_cmp_lt_u32 s44, 63
	s_cbranch_scc1 .Ldense_loop
; #define SBAR() __builtin_amdgcn_sched_barrier(0)
; #define RESC(a) do { if (__any((a) < 1.f)) { if (hi == 0) al_l[r32] = (a); asm volatile("s_waitcnt lgkmcnt(0)" ::: "memory"); \
;     _Pragma("unroll") for (int d = 0; d < 4; ++d) _Pragma("unroll") for (int r = 0; r < 16; ++r) o[d][r] *= al_l[crow(r, hi)]; } } while (0)
;     ...
;   PAIR_FULL(0, 1, NP - 1);
;   { SBAR(); qkt(pB0, pB1, KSUB(1, 1), qr, r32, hi);
;     finishSM(pA0, pA1, alA, l_reg, pa0, pa1, pa2, pa3); SBAR();
;     pv_d0(o, VSUB(1, 0), pa0, pa1, pa2, pa3); partialSM(pB0, pB1, m_reg, mnB, alB);
;     RESC(alB);
;     finishSM(pB0, pB1, alB, l_reg, pa0, pa1, pa2, pa3); SBAR();
;     pv_d0(o, VSUB(1, 1), pa0, pa1, pa2, pa3); }
	v_mfma_f32_16x16x32_bf16 v[128:131], v[200:203], v[96:99], 0
	v_add_f32_e32 v169, v169, v64
	s_add_i32 m0, s32, 0x18000
	s_nop 0
	global_load_lds_dwordx4 v181, s[0:1]
	v_mfma_f32_16x16x32_bf16 v[132:135], v[200:203], v[112:115], 0
	ds_read_b128 v[200:203], v174 offset:16384
	v_add_f32_e32 v169, v169, v65
	v_cvt_pk_bf16_f32 v184, v64, v65
	v_mfma_f32_16x16x32_bf16 v[136:139], v[204:207], v[96:99], 0
	v_add_f32_e32 v169, v169, v66
	v_mfma_f32_16x16x32_bf16 v[140:143], v[204:207], v[112:115], 0
	ds_read_b128 v[204:207], v174 offset:20480
	v_add_f32_e32 v169, v169, v67
	v_cvt_pk_bf16_f32 v185, v66, v67
	s_waitcnt lgkmcnt(7)
	v_mfma_f32_16x16x32_bf16 v[144:147], v[208:211], v[96:99], 0
	v_add_f32_e32 v222, v222, v68
	s_add_i32 m0, s32, 0x1a000
	s_nop 0
	global_load_lds_dwordx4 v181, s[4:5]
	s_add_u32 s0, s0, 0x150000
	s_addc_u32 s1, s1, 0
	s_add_u32 s4, s4, 0x150000
	s_addc_u32 s5, s5, 0
	v_mfma_f32_16x16x32_bf16 v[148:151], v[208:211], v[112:115], 0
	ds_read_b128 v[208:211], v174 offset:24576
	v_add_f32_e32 v222, v222, v69
	v_cvt_pk_bf16_f32 v186, v72, v73
	s_waitcnt lgkmcnt(7)
	v_mfma_f32_16x16x32_bf16 v[152:155], v[212:215], v[96:99], 0
	v_add_f32_e32 v222, v222, v70
	v_mfma_f32_16x16x32_bf16 v[156:159], v[212:215], v[112:115], 0
	ds_read_b128 v[212:215], v174 offset:28672
	v_add_f32_e32 v222, v222, v71
	v_cvt_pk_bf16_f32 v187, v74, v75
	s_waitcnt lgkmcnt(7)
	v_mfma_f32_16x16x32_bf16 v[128:131], v[230:233], v[100:103], v[128:131]
	v_add_f32_e32 v169, v169, v72
	v_mfma_f32_16x16x32_bf16 v[132:135], v[230:233], v[116:119], v[132:135]
	ds_read_b128 v[230:233], v175 offset:16384
	v_add_f32_e32 v169, v169, v73
	v_cvt_pk_bf16_f32 v188, v80, v81
	s_waitcnt lgkmcnt(7)
	v_mfma_f32_16x16x32_bf16 v[136:139], v[234:237], v[100:103], v[136:139]
	v_add_f32_e32 v169, v169, v74
	v_mfma_f32_16x16x32_bf16 v[140:143], v[234:237], v[116:119], v[140:143]
	ds_read_b128 v[234:237], v175 offset:20480
	v_add_f32_e32 v169, v169, v75
	v_cvt_pk_bf16_f32 v189, v82, v83
	s_waitcnt lgkmcnt(7)
	v_mfma_f32_16x16x32_bf16 v[144:147], v[238:241], v[100:103], v[144:147]
	v_add_f32_e32 v222, v222, v76
	v_mfma_f32_16x16x32_bf16 v[148:151], v[238:241], v[116:119], v[148:151]
	ds_read_b128 v[238:241], v175 offset:24576
	v_add_f32_e32 v222, v222, v77
	v_cvt_pk_bf16_f32 v190, v88, v89
	s_waitcnt lgkmcnt(7)
	v_mfma_f32_16x16x32_bf16 v[152:155], v[242:245], v[100:103], v[152:155]
	v_add_f32_e32 v222, v222, v78
	v_mfma_f32_16x16x32_bf16 v[156:159], v[242:245], v[116:119], v[156:159]
	ds_read_b128 v[242:245], v175 offset:28672
	v_add_f32_e32 v222, v222, v79
	v_cvt_pk_bf16_f32 v191, v90, v91
	s_waitcnt lgkmcnt(7)
	v_mfma_f32_16x16x32_bf16 v[128:131], v[200:203], v[104:107], v[128:131]
	v_add_f32_e32 v169, v169, v80
	v_mfma_f32_16x16x32_bf16 v[132:135], v[200:203], v[120:123], v[132:135]
	v_add_f32_e32 v169, v169, v81
	v_cvt_pk_bf16_f32 v192, v68, v69
	s_waitcnt lgkmcnt(6)
	v_mfma_f32_16x16x32_bf16 v[136:139], v[204:207], v[104:107], v[136:139]
	v_add_f32_e32 v169, v169, v82
	v_mfma_f32_16x16x32_bf16 v[140:143], v[204:207], v[120:123], v[140:143]
	v_add_f32_e32 v169, v169, v83
	v_cvt_pk_bf16_f32 v193, v70, v71
	s_waitcnt lgkmcnt(5)
	v_mfma_f32_16x16x32_bf16 v[144:147], v[208:211], v[104:107], v[144:147]
	v_add_f32_e32 v222, v222, v84
	v_mfma_f32_16x16x32_bf16 v[148:151], v[208:211], v[120:123], v[148:151]
	v_add_f32_e32 v222, v222, v85
	v_cvt_pk_bf16_f32 v194, v76, v77
	s_waitcnt lgkmcnt(4)
	v_mfma_f32_16x16x32_bf16 v[152:155], v[212:215], v[104:107], v[152:155]
	ds_read_b64_tr_b16 v[200:201], v176 offset:0
	ds_read_b64_tr_b16 v[202:203], v176 offset:4096
	v_add_f32_e32 v222, v222, v86
	v_mfma_f32_16x16x32_bf16 v[156:159], v[212:215], v[120:123], v[156:159]
	v_add_f32_e32 v222, v222, v87
	v_cvt_pk_bf16_f32 v195, v78, v79
	s_waitcnt lgkmcnt(5)
	v_mfma_f32_16x16x32_bf16 v[128:131], v[230:233], v[108:111], v[128:131]
	ds_read_b64_tr_b16 v[204:205], v177 offset:0
	ds_read_b64_tr_b16 v[206:207], v177 offset:4096
	v_add_f32_e32 v169, v169, v88
	v_mfma_f32_16x16x32_bf16 v[132:135], v[230:233], v[124:127], v[132:135]
	v_add_f32_e32 v169, v169, v89
	v_cvt_pk_bf16_f32 v196, v84, v85
	s_waitcnt lgkmcnt(6)
	v_mfma_f32_16x16x32_bf16 v[136:139], v[234:237], v[108:111], v[136:139]
	ds_read_b64_tr_b16 v[208:209], v178 offset:0
	ds_read_b64_tr_b16 v[210:211], v178 offset:4096
	v_add_f32_e32 v169, v169, v90
	v_mfma_f32_16x16x32_bf16 v[140:143], v[234:237], v[124:127], v[140:143]
	v_add_f32_e32 v169, v169, v91
	v_cvt_pk_bf16_f32 v197, v86, v87
	s_waitcnt lgkmcnt(7)
	v_mfma_f32_16x16x32_bf16 v[144:147], v[238:241], v[108:111], v[144:147]
	ds_read_b64_tr_b16 v[212:213], v179 offset:0
	ds_read_b64_tr_b16 v[214:215], v179 offset:4096
	v_add_f32_e32 v222, v222, v92
	v_mfma_f32_16x16x32_bf16 v[148:151], v[238:241], v[124:127], v[148:151]
	v_add_f32_e32 v222, v222, v93
	v_cvt_pk_bf16_f32 v198, v92, v93
	s_waitcnt lgkmcnt(8)
	v_mfma_f32_16x16x32_bf16 v[152:155], v[242:245], v[108:111], v[152:155]
	ds_read_b64_tr_b16 v[230:231], v180 offset:0
	ds_read_b64_tr_b16 v[232:233], v180 offset:4096
	v_add_f32_e32 v222, v222, v94
	v_mfma_f32_16x16x32_bf16 v[156:159], v[242:245], v[124:127], v[156:159]
	v_add_f32_e32 v222, v222, v95
	v_cvt_pk_bf16_f32 v199, v94, v95
	s_waitcnt lgkmcnt(8)
	v_mfma_f32_16x16x32_bf16 v[0:3], v[200:203], v[184:187], v[0:3]
	v_exp_f32_e32 v128, v128
	v_mfma_f32_16x16x32_bf16 v[32:35], v[200:203], v[192:195], v[32:35]
	ds_read_b64_tr_b16 v[234:235], v182 offset:0
	ds_read_b64_tr_b16 v[236:237], v182 offset:4096
	v_exp_f32_e32 v129, v129
	s_waitcnt lgkmcnt(8)
; #define SBAR() __builtin_amdgcn_sched_barrier(0)
; #define RESC(a) do { if (__any((a) < 1.f)) { if (hi == 0) al_l[r32] = (a); asm volatile("s_waitcnt lgkmcnt(0)" ::: "memory"); \
;     _Pragma("unroll") for (int d = 0; d < 4; ++d) _Pragma("unroll") for (int r = 0; r < 16; ++r) o[d][r] *= al_l[crow(r, hi)]; } } while (0)
;     ...
;   PAIR_FULL(0, 1, NP - 1);
;   { SBAR(); qkt(pB0, pB1, KSUB(1, 1), qr, r32, hi);
;     finishSM(pA0, pA1, alA, l_reg, pa0, pa1, pa2, pa3); SBAR();
;     pv_d0(o, VSUB(1, 0), pa0, pa1, pa2, pa3); partialSM(pB0, pB1, m_reg, mnB, alB);
;     RESC(alB);
;     finishSM(pB0, pB1, alB, l_reg, pa0, pa1, pa2, pa3); SBAR();
;     pv_d0(o, VSUB(1, 1), pa0, pa1, pa2, pa3); }
	v_mfma_f32_16x16x32_bf16 v[4:7], v[204:207], v[184:187], v[4:7]
	v_exp_f32_e32 v130, v130
	v_mfma_f32_16x16x32_bf16 v[36:39], v[204:207], v[192:195], v[36:39]
	ds_read_b64_tr_b16 v[238:239], v216 offset:0
	ds_read_b64_tr_b16 v[240:241], v216 offset:4096
	v_exp_f32_e32 v131, v131
	s_waitcnt lgkmcnt(8)
	v_mfma_f32_16x16x32_bf16 v[8:11], v[208:211], v[184:187], v[8:11]
	v_exp_f32_e32 v132, v132
	v_mfma_f32_16x16x32_bf16 v[40:43], v[208:211], v[192:195], v[40:43]
	ds_read_b64_tr_b16 v[242:243], v217 offset:0
	ds_read_b64_tr_b16 v[244:245], v217 offset:4096
	v_exp_f32_e32 v133, v133
	s_waitcnt lgkmcnt(8)
	v_mfma_f32_16x16x32_bf16 v[12:15], v[212:215], v[184:187], v[12:15]
	v_exp_f32_e32 v134, v134
	v_mfma_f32_16x16x32_bf16 v[44:47], v[212:215], v[192:195], v[44:47]
	ds_read_b64_tr_b16 v[200:201], v176 offset:8192
	ds_read_b64_tr_b16 v[202:203], v176 offset:12288
	v_exp_f32_e32 v135, v135
	s_waitcnt lgkmcnt(8)
	v_mfma_f32_16x16x32_bf16 v[16:19], v[230:233], v[184:187], v[16:19]
	v_exp_f32_e32 v136, v136
	v_mfma_f32_16x16x32_bf16 v[48:51], v[230:233], v[192:195], v[48:51]
	ds_read_b64_tr_b16 v[204:205], v177 offset:8192
	ds_read_b64_tr_b16 v[206:207], v177 offset:12288
	v_exp_f32_e32 v137, v137
	s_waitcnt lgkmcnt(8)
	v_mfma_f32_16x16x32_bf16 v[20:23], v[234:237], v[184:187], v[20:23]
	v_exp_f32_e32 v138, v138
	v_mfma_f32_16x16x32_bf16 v[52:55], v[234:237], v[192:195], v[52:55]
	ds_read_b64_tr_b16 v[208:209], v178 offset:8192
	ds_read_b64_tr_b16 v[210:211], v178 offset:12288
	v_exp_f32_e32 v139, v139
	s_waitcnt lgkmcnt(8)
	v_mfma_f32_16x16x32_bf16 v[24:27], v[238:241], v[184:187], v[24:27]
	v_exp_f32_e32 v140, v140
	v_mfma_f32_16x16x32_bf16 v[56:59], v[238:241], v[192:195], v[56:59]
	ds_read_b64_tr_b16 v[212:213], v179 offset:8192
	ds_read_b64_tr_b16 v[214:215], v179 offset:12288
	v_exp_f32_e32 v141, v141
	s_waitcnt lgkmcnt(8)
	v_mfma_f32_16x16x32_bf16 v[28:31], v[242:245], v[184:187], v[28:31]
	v_exp_f32_e32 v142, v142
	v_mfma_f32_16x16x32_bf16 v[60:63], v[242:245], v[192:195], v[60:63]
	ds_read_b64_tr_b16 v[230:231], v180 offset:8192
	ds_read_b64_tr_b16 v[232:233], v180 offset:12288
	v_exp_f32_e32 v143, v143
	s_waitcnt lgkmcnt(8)
	v_mfma_f32_16x16x32_bf16 v[0:3], v[200:203], v[188:191], v[0:3]
	v_exp_f32_e32 v144, v144
	v_mfma_f32_16x16x32_bf16 v[32:35], v[200:203], v[196:199], v[32:35]
	ds_read_b64_tr_b16 v[234:235], v182 offset:8192
	ds_read_b64_tr_b16 v[236:237], v182 offset:12288
	ds_read_b128 v[200:203], v172 offset:32768
	v_exp_f32_e32 v145, v145
	s_waitcnt lgkmcnt(9)
	v_mfma_f32_16x16x32_bf16 v[4:7], v[204:207], v[188:191], v[4:7]
	v_exp_f32_e32 v146, v146
	v_mfma_f32_16x16x32_bf16 v[36:39], v[204:207], v[196:199], v[36:39]
	ds_read_b64_tr_b16 v[238:239], v216 offset:8192
	ds_read_b64_tr_b16 v[240:241], v216 offset:12288
	ds_read_b128 v[204:207], v172 offset:36864
	v_exp_f32_e32 v147, v147
	s_waitcnt lgkmcnt(10)
	v_mfma_f32_16x16x32_bf16 v[8:11], v[208:211], v[188:191], v[8:11]
	v_exp_f32_e32 v148, v148
	v_mfma_f32_16x16x32_bf16 v[40:43], v[208:211], v[196:199], v[40:43]
	ds_read_b64_tr_b16 v[242:243], v217 offset:8192
	ds_read_b64_tr_b16 v[244:245], v217 offset:12288
	ds_read_b128 v[208:211], v172 offset:40960
	v_exp_f32_e32 v149, v149
	s_waitcnt lgkmcnt(11)
	v_mfma_f32_16x16x32_bf16 v[12:15], v[212:215], v[188:191], v[12:15]
	v_exp_f32_e32 v150, v150
	v_mfma_f32_16x16x32_bf16 v[44:47], v[212:215], v[196:199], v[44:47]
	ds_read_b128 v[212:215], v172 offset:45056
	v_exp_f32_e32 v151, v151
	s_waitcnt lgkmcnt(10)
	v_mfma_f32_16x16x32_bf16 v[16:19], v[230:233], v[188:191], v[16:19]
	v_exp_f32_e32 v152, v152
	v_mfma_f32_16x16x32_bf16 v[48:51], v[230:233], v[196:199], v[48:51]
	ds_read_b128 v[230:233], v173 offset:32768
	v_exp_f32_e32 v153, v153
	s_waitcnt lgkmcnt(9)
	v_mfma_f32_16x16x32_bf16 v[20:23], v[234:237], v[188:191], v[20:23]
	v_exp_f32_e32 v154, v154
	v_mfma_f32_16x16x32_bf16 v[52:55], v[234:237], v[196:199], v[52:55]
	ds_read_b128 v[234:237], v173 offset:36864
	v_exp_f32_e32 v155, v155
	s_waitcnt lgkmcnt(7)
	v_mfma_f32_16x16x32_bf16 v[24:27], v[238:241], v[188:191], v[24:27]
	v_exp_f32_e32 v156, v156
	v_mfma_f32_16x16x32_bf16 v[56:59], v[238:241], v[196:199], v[56:59]
	ds_read_b128 v[238:241], v173 offset:40960
	v_exp_f32_e32 v157, v157
	s_waitcnt lgkmcnt(5)
	v_mfma_f32_16x16x32_bf16 v[28:31], v[242:245], v[188:191], v[28:31]
	v_exp_f32_e32 v158, v158
	v_mfma_f32_16x16x32_bf16 v[60:63], v[242:245], v[196:199], v[60:63]
	ds_read_b128 v[242:245], v173 offset:45056
	v_exp_f32_e32 v159, v159
	s_waitcnt vmcnt(2)
	s_barrier
; #define SBAR() __builtin_amdgcn_sched_barrier(0)
; #define RESC(a) do { if (__any((a) < 1.f)) { if (hi == 0) al_l[r32] = (a); asm volatile("s_waitcnt lgkmcnt(0)" ::: "memory"); \
;     _Pragma("unroll") for (int d = 0; d < 4; ++d) _Pragma("unroll") for (int r = 0; r < 16; ++r) o[d][r] *= al_l[crow(r, hi)]; } } while (0)
;     ...
;   PAIR_FULL(0, 1, NP - 1);
;   { SBAR(); qkt(pB0, pB1, KSUB(1, 1), qr, r32, hi);
;     finishSM(pA0, pA1, alA, l_reg, pa0, pa1, pa2, pa3); SBAR();
;     pv_d0(o, VSUB(1, 0), pa0, pa1, pa2, pa3); partialSM(pB0, pB1, m_reg, mnB, alB);
;     RESC(alB);
;     finishSM(pB0, pB1, alB, l_reg, pa0, pa1, pa2, pa3); SBAR();
;     pv_d0(o, VSUB(1, 1), pa0, pa1, pa2, pa3); }
	v_mfma_f32_16x16x32_bf16 v[64:67], v[200:203], v[96:99], 0
	v_add_f32_e32 v169, v169, v128
	s_add_i32 m0, s32, 0x1c000
	s_nop 0
	global_load_lds_dwordx4 v181, s[0:1]
	v_mfma_f32_16x16x32_bf16 v[68:71], v[200:203], v[112:115], 0
	ds_read_b128 v[200:203], v174 offset:32768
	v_add_f32_e32 v169, v169, v129
	v_cvt_pk_bf16_f32 v184, v128, v129
	v_mfma_f32_16x16x32_bf16 v[72:75], v[204:207], v[96:99], 0
	v_add_f32_e32 v169, v169, v130
	v_mfma_f32_16x16x32_bf16 v[76:79], v[204:207], v[112:115], 0
	ds_read_b128 v[204:207], v174 offset:36864
	v_add_f32_e32 v169, v169, v131
	v_cvt_pk_bf16_f32 v185, v130, v131
	s_waitcnt lgkmcnt(7)
	v_mfma_f32_16x16x32_bf16 v[80:83], v[208:211], v[96:99], 0
	v_add_f32_e32 v222, v222, v132
	s_add_i32 m0, s32, 0x1e000
	s_nop 0
	global_load_lds_dwordx4 v181, s[4:5]
	s_add_u32 s0, s0, 0x150000
	s_addc_u32 s1, s1, 0
	s_add_u32 s4, s4, 0x150000
	s_addc_u32 s5, s5, 0
	v_mfma_f32_16x16x32_bf16 v[84:87], v[208:211], v[112:115], 0
	ds_read_b128 v[208:211], v174 offset:40960
	v_add_f32_e32 v222, v222, v133
	v_cvt_pk_bf16_f32 v186, v136, v137
	s_waitcnt lgkmcnt(7)
	v_mfma_f32_16x16x32_bf16 v[88:91], v[212:215], v[96:99], 0
	v_add_f32_e32 v222, v222, v134
	v_mfma_f32_16x16x32_bf16 v[92:95], v[212:215], v[112:115], 0
	ds_read_b128 v[212:215], v174 offset:45056
	v_add_f32_e32 v222, v222, v135
	v_cvt_pk_bf16_f32 v187, v138, v139
	s_waitcnt lgkmcnt(7)
	v_mfma_f32_16x16x32_bf16 v[64:67], v[230:233], v[100:103], v[64:67]
	v_add_f32_e32 v169, v169, v136
	v_mfma_f32_16x16x32_bf16 v[68:71], v[230:233], v[116:119], v[68:71]
	ds_read_b128 v[230:233], v175 offset:32768
	v_add_f32_e32 v169, v169, v137
	v_cvt_pk_bf16_f32 v188, v144, v145
	s_waitcnt lgkmcnt(7)
	v_mfma_f32_16x16x32_bf16 v[72:75], v[234:237], v[100:103], v[72:75]
	v_add_f32_e32 v169, v169, v138
	v_mfma_f32_16x16x32_bf16 v[76:79], v[234:237], v[116:119], v[76:79]
	ds_read_b128 v[234:237], v175 offset:36864
	v_add_f32_e32 v169, v169, v139
	v_cvt_pk_bf16_f32 v189, v146, v147
	s_waitcnt lgkmcnt(7)
	v_mfma_f32_16x16x32_bf16 v[80:83], v[238:241], v[100:103], v[80:83]
	v_add_f32_e32 v222, v222, v140
	v_mfma_f32_16x16x32_bf16 v[84:87], v[238:241], v[116:119], v[84:87]
	ds_read_b128 v[238:241], v175 offset:40960
	v_add_f32_e32 v222, v222, v141
	v_cvt_pk_bf16_f32 v190, v152, v153
	s_waitcnt lgkmcnt(7)
	v_mfma_f32_16x16x32_bf16 v[88:91], v[242:245], v[100:103], v[88:91]
	v_add_f32_e32 v222, v222, v142
	v_mfma_f32_16x16x32_bf16 v[92:95], v[242:245], v[116:119], v[92:95]
	ds_read_b128 v[242:245], v175 offset:45056
	v_add_f32_e32 v222, v222, v143
	v_cvt_pk_bf16_f32 v191, v154, v155
	s_waitcnt lgkmcnt(7)
	v_mfma_f32_16x16x32_bf16 v[64:67], v[200:203], v[104:107], v[64:67]
	v_add_f32_e32 v169, v169, v144
	v_mfma_f32_16x16x32_bf16 v[68:71], v[200:203], v[120:123], v[68:71]
	v_add_f32_e32 v169, v169, v145
	v_cvt_pk_bf16_f32 v192, v132, v133
	s_waitcnt lgkmcnt(6)
	v_mfma_f32_16x16x32_bf16 v[72:75], v[204:207], v[104:107], v[72:75]
	v_add_f32_e32 v169, v169, v146
	v_mfma_f32_16x16x32_bf16 v[76:79], v[204:207], v[120:123], v[76:79]
	v_add_f32_e32 v169, v169, v147
	v_cvt_pk_bf16_f32 v193, v134, v135
	s_waitcnt lgkmcnt(5)
	v_mfma_f32_16x16x32_bf16 v[80:83], v[208:211], v[104:107], v[80:83]
	v_add_f32_e32 v222, v222, v148
	v_mfma_f32_16x16x32_bf16 v[84:87], v[208:211], v[120:123], v[84:87]
	v_add_f32_e32 v222, v222, v149
	v_cvt_pk_bf16_f32 v194, v140, v141
	s_waitcnt lgkmcnt(4)
	v_mfma_f32_16x16x32_bf16 v[88:91], v[212:215], v[104:107], v[88:91]
	ds_read_b64_tr_b16 v[200:201], v176 offset:16384
	ds_read_b64_tr_b16 v[202:203], v176 offset:20480
	v_add_f32_e32 v222, v222, v150
	v_mfma_f32_16x16x32_bf16 v[92:95], v[212:215], v[120:123], v[92:95]
	v_add_f32_e32 v222, v222, v151
	v_cvt_pk_bf16_f32 v195, v142, v143
	s_waitcnt lgkmcnt(5)
	v_mfma_f32_16x16x32_bf16 v[64:67], v[230:233], v[108:111], v[64:67]
	ds_read_b64_tr_b16 v[204:205], v177 offset:16384
	ds_read_b64_tr_b16 v[206:207], v177 offset:20480
	v_add_f32_e32 v169, v169, v152
	v_mfma_f32_16x16x32_bf16 v[68:71], v[230:233], v[124:127], v[68:71]
	v_add_f32_e32 v169, v169, v153
	v_cvt_pk_bf16_f32 v196, v148, v149
	s_waitcnt lgkmcnt(6)
	v_mfma_f32_16x16x32_bf16 v[72:75], v[234:237], v[108:111], v[72:75]
	ds_read_b64_tr_b16 v[208:209], v178 offset:16384
	ds_read_b64_tr_b16 v[210:211], v178 offset:20480
	v_add_f32_e32 v169, v169, v154
	v_mfma_f32_16x16x32_bf16 v[76:79], v[234:237], v[124:127], v[76:79]
	v_add_f32_e32 v169, v169, v155
	v_cvt_pk_bf16_f32 v197, v150, v151
	s_waitcnt lgkmcnt(7)
	v_mfma_f32_16x16x32_bf16 v[80:83], v[238:241], v[108:111], v[80:83]
	ds_read_b64_tr_b16 v[212:213], v179 offset:16384
	ds_read_b64_tr_b16 v[214:215], v179 offset:20480
	v_add_f32_e32 v222, v222, v156
	v_mfma_f32_16x16x32_bf16 v[84:87], v[238:241], v[124:127], v[84:87]
	v_add_f32_e32 v222, v222, v157
	v_cvt_pk_bf16_f32 v198, v156, v157
	s_waitcnt lgkmcnt(8)
	v_mfma_f32_16x16x32_bf16 v[88:91], v[242:245], v[108:111], v[88:91]
	ds_read_b64_tr_b16 v[230:231], v180 offset:16384
	ds_read_b64_tr_b16 v[232:233], v180 offset:20480
	v_add_f32_e32 v222, v222, v158
	v_mfma_f32_16x16x32_bf16 v[92:95], v[242:245], v[124:127], v[92:95]
	v_add_f32_e32 v222, v222, v159
	v_cvt_pk_bf16_f32 v199, v158, v159
	s_waitcnt lgkmcnt(8)
	v_mfma_f32_16x16x32_bf16 v[0:3], v[200:203], v[184:187], v[0:3]
	v_exp_f32_e32 v64, v64
	v_mfma_f32_16x16x32_bf16 v[32:35], v[200:203], v[192:195], v[32:35]
	ds_read_b64_tr_b16 v[234:235], v182 offset:16384
	ds_read_b64_tr_b16 v[236:237], v182 offset:20480
	v_exp_f32_e32 v65, v65
	s_waitcnt lgkmcnt(8)
	v_mfma_f32_16x16x32_bf16 v[4:7], v[204:207], v[184:187], v[4:7]
	v_exp_f32_e32 v66, v66
	v_mfma_f32_16x16x32_bf16 v[36:39], v[204:207], v[192:195], v[36:39]
	ds_read_b64_tr_b16 v[238:239], v216 offset:16384
	ds_read_b64_tr_b16 v[240:241], v216 offset:20480
	v_exp_f32_e32 v67, v67
	s_waitcnt lgkmcnt(8)
; #define SBAR() __builtin_amdgcn_sched_barrier(0)
; #define RESC(a) do { if (__any((a) < 1.f)) { if (hi == 0) al_l[r32] = (a); asm volatile("s_waitcnt lgkmcnt(0)" ::: "memory"); \
;     _Pragma("unroll") for (int d = 0; d < 4; ++d) _Pragma("unroll") for (int r = 0; r < 16; ++r) o[d][r] *= al_l[crow(r, hi)]; } } while (0)
;     ...
;   PAIR_FULL(0, 1, NP - 1);
;   { SBAR(); qkt(pB0, pB1, KSUB(1, 1), qr, r32, hi);
;     finishSM(pA0, pA1, alA, l_reg, pa0, pa1, pa2, pa3); SBAR();
;     pv_d0(o, VSUB(1, 0), pa0, pa1, pa2, pa3); partialSM(pB0, pB1, m_reg, mnB, alB);
;     RESC(alB);
;     finishSM(pB0, pB1, alB, l_reg, pa0, pa1, pa2, pa3); SBAR();
;     pv_d0(o, VSUB(1, 1), pa0, pa1, pa2, pa3); }
	v_mfma_f32_16x16x32_bf16 v[8:11], v[208:211], v[184:187], v[8:11]
	v_exp_f32_e32 v68, v68
	v_mfma_f32_16x16x32_bf16 v[40:43], v[208:211], v[192:195], v[40:43]
	ds_read_b64_tr_b16 v[242:243], v217 offset:16384
	ds_read_b64_tr_b16 v[244:245], v217 offset:20480
	v_exp_f32_e32 v69, v69
	s_waitcnt lgkmcnt(8)
	v_mfma_f32_16x16x32_bf16 v[12:15], v[212:215], v[184:187], v[12:15]
	v_exp_f32_e32 v70, v70
	v_mfma_f32_16x16x32_bf16 v[44:47], v[212:215], v[192:195], v[44:47]
	ds_read_b64_tr_b16 v[200:201], v176 offset:24576
	ds_read_b64_tr_b16 v[202:203], v176 offset:28672
	v_exp_f32_e32 v71, v71
	s_waitcnt lgkmcnt(8)
	v_mfma_f32_16x16x32_bf16 v[16:19], v[230:233], v[184:187], v[16:19]
	v_exp_f32_e32 v72, v72
	v_mfma_f32_16x16x32_bf16 v[48:51], v[230:233], v[192:195], v[48:51]
	ds_read_b64_tr_b16 v[204:205], v177 offset:24576
	ds_read_b64_tr_b16 v[206:207], v177 offset:28672
	v_exp_f32_e32 v73, v73
	s_waitcnt lgkmcnt(8)
	v_mfma_f32_16x16x32_bf16 v[20:23], v[234:237], v[184:187], v[20:23]
	v_exp_f32_e32 v74, v74
	v_mfma_f32_16x16x32_bf16 v[52:55], v[234:237], v[192:195], v[52:55]
	ds_read_b64_tr_b16 v[208:209], v178 offset:24576
	ds_read_b64_tr_b16 v[210:211], v178 offset:28672
	v_exp_f32_e32 v75, v75
	s_waitcnt lgkmcnt(8)
	v_mfma_f32_16x16x32_bf16 v[24:27], v[238:241], v[184:187], v[24:27]
	v_exp_f32_e32 v76, v76
	v_mfma_f32_16x16x32_bf16 v[56:59], v[238:241], v[192:195], v[56:59]
	ds_read_b64_tr_b16 v[212:213], v179 offset:24576
	ds_read_b64_tr_b16 v[214:215], v179 offset:28672
	v_exp_f32_e32 v77, v77
	s_waitcnt lgkmcnt(8)
	v_mfma_f32_16x16x32_bf16 v[28:31], v[242:245], v[184:187], v[28:31]
	v_exp_f32_e32 v78, v78
	v_mfma_f32_16x16x32_bf16 v[60:63], v[242:245], v[192:195], v[60:63]
	ds_read_b64_tr_b16 v[230:231], v180 offset:24576
	ds_read_b64_tr_b16 v[232:233], v180 offset:28672
	v_exp_f32_e32 v79, v79
	s_waitcnt lgkmcnt(8)
	v_mfma_f32_16x16x32_bf16 v[0:3], v[200:203], v[188:191], v[0:3]
	v_exp_f32_e32 v80, v80
	v_mfma_f32_16x16x32_bf16 v[32:35], v[200:203], v[196:199], v[32:35]
	ds_read_b64_tr_b16 v[234:235], v182 offset:24576
	ds_read_b64_tr_b16 v[236:237], v182 offset:28672
	ds_read_b128 v[200:203], v172 offset:49152
	v_exp_f32_e32 v81, v81
	s_waitcnt lgkmcnt(9)
	v_mfma_f32_16x16x32_bf16 v[4:7], v[204:207], v[188:191], v[4:7]
	v_exp_f32_e32 v82, v82
	v_mfma_f32_16x16x32_bf16 v[36:39], v[204:207], v[196:199], v[36:39]
	ds_read_b64_tr_b16 v[238:239], v216 offset:24576
	ds_read_b64_tr_b16 v[240:241], v216 offset:28672
	ds_read_b128 v[204:207], v172 offset:53248
	v_exp_f32_e32 v83, v83
	s_waitcnt lgkmcnt(10)
	v_mfma_f32_16x16x32_bf16 v[8:11], v[208:211], v[188:191], v[8:11]
	v_exp_f32_e32 v84, v84
	v_mfma_f32_16x16x32_bf16 v[40:43], v[208:211], v[196:199], v[40:43]
	ds_read_b64_tr_b16 v[242:243], v217 offset:24576
	ds_read_b64_tr_b16 v[244:245], v217 offset:28672
	ds_read_b128 v[208:211], v172 offset:57344
	v_exp_f32_e32 v85, v85
	s_waitcnt lgkmcnt(11)
	v_mfma_f32_16x16x32_bf16 v[12:15], v[212:215], v[188:191], v[12:15]
	v_exp_f32_e32 v86, v86
	v_mfma_f32_16x16x32_bf16 v[44:47], v[212:215], v[196:199], v[44:47]
	ds_read_b128 v[212:215], v172 offset:61440
	v_exp_f32_e32 v87, v87
	s_waitcnt lgkmcnt(10)
	v_mfma_f32_16x16x32_bf16 v[16:19], v[230:233], v[188:191], v[16:19]
	v_exp_f32_e32 v88, v88
	v_mfma_f32_16x16x32_bf16 v[48:51], v[230:233], v[196:199], v[48:51]
	ds_read_b128 v[230:233], v173 offset:49152
	v_exp_f32_e32 v89, v89
	s_waitcnt lgkmcnt(9)
	v_mfma_f32_16x16x32_bf16 v[20:23], v[234:237], v[188:191], v[20:23]
	v_exp_f32_e32 v90, v90
	v_mfma_f32_16x16x32_bf16 v[52:55], v[234:237], v[196:199], v[52:55]
	ds_read_b128 v[234:237], v173 offset:53248
	v_exp_f32_e32 v91, v91
	s_waitcnt lgkmcnt(7)
	v_mfma_f32_16x16x32_bf16 v[24:27], v[238:241], v[188:191], v[24:27]
	v_exp_f32_e32 v92, v92
	v_mfma_f32_16x16x32_bf16 v[56:59], v[238:241], v[196:199], v[56:59]
	ds_read_b128 v[238:241], v173 offset:57344
	v_exp_f32_e32 v93, v93
	s_waitcnt lgkmcnt(5)
	v_mfma_f32_16x16x32_bf16 v[28:31], v[242:245], v[188:191], v[28:31]
	v_exp_f32_e32 v94, v94
	v_mfma_f32_16x16x32_bf16 v[60:63], v[242:245], v[196:199], v[60:63]
	ds_read_b128 v[242:245], v173 offset:61440
	v_exp_f32_e32 v95, v95
	s_waitcnt vmcnt(2)
	s_barrier
	v_mfma_f32_16x16x32_bf16 v[128:131], v[200:203], v[96:99], 0
	v_add_f32_e32 v169, v169, v64
	v_mfma_f32_16x16x32_bf16 v[132:135], v[200:203], v[112:115], 0
	ds_read_b128 v[200:203], v174 offset:49152
	v_add_f32_e32 v169, v169, v65
	v_cvt_pk_bf16_f32 v184, v64, v65
	v_mfma_f32_16x16x32_bf16 v[136:139], v[204:207], v[96:99], 0
	v_add_f32_e32 v169, v169, v66
	v_mfma_f32_16x16x32_bf16 v[140:143], v[204:207], v[112:115], 0
	ds_read_b128 v[204:207], v174 offset:53248
	v_add_f32_e32 v169, v169, v67
	v_cvt_pk_bf16_f32 v185, v66, v67
	s_waitcnt lgkmcnt(7)
	v_mfma_f32_16x16x32_bf16 v[144:147], v[208:211], v[96:99], 0
	v_add_f32_e32 v222, v222, v68
	v_mfma_f32_16x16x32_bf16 v[148:151], v[208:211], v[112:115], 0
	ds_read_b128 v[208:211], v174 offset:57344
	v_add_f32_e32 v222, v222, v69
	v_cvt_pk_bf16_f32 v186, v72, v73
	s_waitcnt lgkmcnt(7)
	v_mfma_f32_16x16x32_bf16 v[152:155], v[212:215], v[96:99], 0
	v_add_f32_e32 v222, v222, v70
	v_mfma_f32_16x16x32_bf16 v[156:159], v[212:215], v[112:115], 0
	ds_read_b128 v[212:215], v174 offset:61440
	v_add_f32_e32 v222, v222, v71
	v_cvt_pk_bf16_f32 v187, v74, v75
	s_waitcnt lgkmcnt(7)
	v_mfma_f32_16x16x32_bf16 v[128:131], v[230:233], v[100:103], v[128:131]
	v_add_f32_e32 v169, v169, v72
	v_mfma_f32_16x16x32_bf16 v[132:135], v[230:233], v[116:119], v[132:135]
	ds_read_b128 v[230:233], v175 offset:49152
	v_add_f32_e32 v169, v169, v73
	v_cvt_pk_bf16_f32 v188, v80, v81
	s_waitcnt lgkmcnt(7)
; #define SBAR() __builtin_amdgcn_sched_barrier(0)
; #define RESC(a) do { if (__any((a) < 1.f)) { if (hi == 0) al_l[r32] = (a); asm volatile("s_waitcnt lgkmcnt(0)" ::: "memory"); \
;     _Pragma("unroll") for (int d = 0; d < 4; ++d) _Pragma("unroll") for (int r = 0; r < 16; ++r) o[d][r] *= al_l[crow(r, hi)]; } } while (0)
;     ...
;   PAIR_FULL(0, 1, NP - 1);
;   { SBAR(); qkt(pB0, pB1, KSUB(1, 1), qr, r32, hi);
;     finishSM(pA0, pA1, alA, l_reg, pa0, pa1, pa2, pa3); SBAR();
;     pv_d0(o, VSUB(1, 0), pa0, pa1, pa2, pa3); partialSM(pB0, pB1, m_reg, mnB, alB);
;     RESC(alB);
;     finishSM(pB0, pB1, alB, l_reg, pa0, pa1, pa2, pa3); SBAR();
;     pv_d0(o, VSUB(1, 1), pa0, pa1, pa2, pa3); }
	v_mfma_f32_16x16x32_bf16 v[136:139], v[234:237], v[100:103], v[136:139]
	v_add_f32_e32 v169, v169, v74
	v_mfma_f32_16x16x32_bf16 v[140:143], v[234:237], v[116:119], v[140:143]
	ds_read_b128 v[234:237], v175 offset:53248
	v_add_f32_e32 v169, v169, v75
	v_cvt_pk_bf16_f32 v189, v82, v83
	s_waitcnt lgkmcnt(7)
	v_mfma_f32_16x16x32_bf16 v[144:147], v[238:241], v[100:103], v[144:147]
	v_add_f32_e32 v222, v222, v76
	v_mfma_f32_16x16x32_bf16 v[148:151], v[238:241], v[116:119], v[148:151]
	ds_read_b128 v[238:241], v175 offset:57344
	v_add_f32_e32 v222, v222, v77
	v_cvt_pk_bf16_f32 v190, v88, v89
	s_waitcnt lgkmcnt(7)
	v_mfma_f32_16x16x32_bf16 v[152:155], v[242:245], v[100:103], v[152:155]
	v_add_f32_e32 v222, v222, v78
	v_mfma_f32_16x16x32_bf16 v[156:159], v[242:245], v[116:119], v[156:159]
	ds_read_b128 v[242:245], v175 offset:61440
	v_add_f32_e32 v222, v222, v79
	v_cvt_pk_bf16_f32 v191, v90, v91
	s_waitcnt lgkmcnt(7)
	v_mfma_f32_16x16x32_bf16 v[128:131], v[200:203], v[104:107], v[128:131]
	v_add_f32_e32 v169, v169, v80
	v_mfma_f32_16x16x32_bf16 v[132:135], v[200:203], v[120:123], v[132:135]
	v_add_f32_e32 v169, v169, v81
	v_cvt_pk_bf16_f32 v192, v68, v69
	s_waitcnt lgkmcnt(6)
	v_mfma_f32_16x16x32_bf16 v[136:139], v[204:207], v[104:107], v[136:139]
	v_add_f32_e32 v169, v169, v82
	v_mfma_f32_16x16x32_bf16 v[140:143], v[204:207], v[120:123], v[140:143]
	v_add_f32_e32 v169, v169, v83
	v_cvt_pk_bf16_f32 v193, v70, v71
	s_waitcnt lgkmcnt(5)
	v_mfma_f32_16x16x32_bf16 v[144:147], v[208:211], v[104:107], v[144:147]
	v_add_f32_e32 v222, v222, v84
	v_mfma_f32_16x16x32_bf16 v[148:151], v[208:211], v[120:123], v[148:151]
	v_add_f32_e32 v222, v222, v85
	v_cvt_pk_bf16_f32 v194, v76, v77
	s_waitcnt lgkmcnt(4)
	v_mfma_f32_16x16x32_bf16 v[152:155], v[212:215], v[104:107], v[152:155]
	ds_read_b64_tr_b16 v[200:201], v176 offset:32768
	ds_read_b64_tr_b16 v[202:203], v176 offset:36864
	v_add_f32_e32 v222, v222, v86
	v_mfma_f32_16x16x32_bf16 v[156:159], v[212:215], v[120:123], v[156:159]
	v_add_f32_e32 v222, v222, v87
	v_cvt_pk_bf16_f32 v195, v78, v79
	s_waitcnt lgkmcnt(5)
	v_mfma_f32_16x16x32_bf16 v[128:131], v[230:233], v[108:111], v[128:131]
	ds_read_b64_tr_b16 v[204:205], v177 offset:32768
	ds_read_b64_tr_b16 v[206:207], v177 offset:36864
	v_add_f32_e32 v169, v169, v88
	v_mfma_f32_16x16x32_bf16 v[132:135], v[230:233], v[124:127], v[132:135]
	v_add_f32_e32 v169, v169, v89
	v_cvt_pk_bf16_f32 v196, v84, v85
	s_waitcnt lgkmcnt(6)
	v_mfma_f32_16x16x32_bf16 v[136:139], v[234:237], v[108:111], v[136:139]
	ds_read_b64_tr_b16 v[208:209], v178 offset:32768
	ds_read_b64_tr_b16 v[210:211], v178 offset:36864
	v_add_f32_e32 v169, v169, v90
	v_mfma_f32_16x16x32_bf16 v[140:143], v[234:237], v[124:127], v[140:143]
	v_add_f32_e32 v169, v169, v91
	v_cvt_pk_bf16_f32 v197, v86, v87
	s_waitcnt lgkmcnt(7)
	v_mfma_f32_16x16x32_bf16 v[144:147], v[238:241], v[108:111], v[144:147]
	ds_read_b64_tr_b16 v[212:213], v179 offset:32768
	ds_read_b64_tr_b16 v[214:215], v179 offset:36864
	v_add_f32_e32 v222, v222, v92
	v_mfma_f32_16x16x32_bf16 v[148:151], v[238:241], v[124:127], v[148:151]
	v_add_f32_e32 v222, v222, v93
	v_cvt_pk_bf16_f32 v198, v92, v93
	s_waitcnt lgkmcnt(8)
	v_mfma_f32_16x16x32_bf16 v[152:155], v[242:245], v[108:111], v[152:155]
	ds_read_b64_tr_b16 v[230:231], v180 offset:32768
	ds_read_b64_tr_b16 v[232:233], v180 offset:36864
	v_add_f32_e32 v222, v222, v94
	v_mfma_f32_16x16x32_bf16 v[156:159], v[242:245], v[124:127], v[156:159]
	v_add_f32_e32 v222, v222, v95
	v_cvt_pk_bf16_f32 v199, v94, v95
	s_waitcnt lgkmcnt(8)
	v_mfma_f32_16x16x32_bf16 v[0:3], v[200:203], v[184:187], v[0:3]
	v_exp_f32_e32 v128, v128
	v_mfma_f32_16x16x32_bf16 v[32:35], v[200:203], v[192:195], v[32:35]
	ds_read_b64_tr_b16 v[234:235], v182 offset:32768
	ds_read_b64_tr_b16 v[236:237], v182 offset:36864
	v_exp_f32_e32 v129, v129
	s_waitcnt lgkmcnt(8)
	v_mfma_f32_16x16x32_bf16 v[4:7], v[204:207], v[184:187], v[4:7]
	v_exp_f32_e32 v130, v130
	v_mfma_f32_16x16x32_bf16 v[36:39], v[204:207], v[192:195], v[36:39]
	ds_read_b64_tr_b16 v[238:239], v216 offset:32768
	ds_read_b64_tr_b16 v[240:241], v216 offset:36864
	v_exp_f32_e32 v131, v131
	s_waitcnt lgkmcnt(8)
	v_mfma_f32_16x16x32_bf16 v[8:11], v[208:211], v[184:187], v[8:11]
	v_exp_f32_e32 v132, v132
	v_mfma_f32_16x16x32_bf16 v[40:43], v[208:211], v[192:195], v[40:43]
	ds_read_b64_tr_b16 v[242:243], v217 offset:32768
	ds_read_b64_tr_b16 v[244:245], v217 offset:36864
	v_exp_f32_e32 v133, v133
	s_waitcnt lgkmcnt(8)
	v_mfma_f32_16x16x32_bf16 v[12:15], v[212:215], v[184:187], v[12:15]
	v_exp_f32_e32 v134, v134
	v_mfma_f32_16x16x32_bf16 v[44:47], v[212:215], v[192:195], v[44:47]
	ds_read_b64_tr_b16 v[200:201], v176 offset:40960
	ds_read_b64_tr_b16 v[202:203], v176 offset:45056
	v_exp_f32_e32 v135, v135
	s_waitcnt lgkmcnt(8)
	v_mfma_f32_16x16x32_bf16 v[16:19], v[230:233], v[184:187], v[16:19]
	v_exp_f32_e32 v136, v136
	v_mfma_f32_16x16x32_bf16 v[48:51], v[230:233], v[192:195], v[48:51]
	ds_read_b64_tr_b16 v[204:205], v177 offset:40960
	ds_read_b64_tr_b16 v[206:207], v177 offset:45056
	v_exp_f32_e32 v137, v137
	s_waitcnt lgkmcnt(8)
	v_mfma_f32_16x16x32_bf16 v[20:23], v[234:237], v[184:187], v[20:23]
	v_exp_f32_e32 v138, v138
	v_mfma_f32_16x16x32_bf16 v[52:55], v[234:237], v[192:195], v[52:55]
	ds_read_b64_tr_b16 v[208:209], v178 offset:40960
	ds_read_b64_tr_b16 v[210:211], v178 offset:45056
	v_exp_f32_e32 v139, v139
	s_waitcnt lgkmcnt(8)
	v_mfma_f32_16x16x32_bf16 v[24:27], v[238:241], v[184:187], v[24:27]
	v_exp_f32_e32 v140, v140
	v_mfma_f32_16x16x32_bf16 v[56:59], v[238:241], v[192:195], v[56:59]
	ds_read_b64_tr_b16 v[212:213], v179 offset:40960
	ds_read_b64_tr_b16 v[214:215], v179 offset:45056
	v_exp_f32_e32 v141, v141
	s_waitcnt lgkmcnt(8)
; #define SBAR() __builtin_amdgcn_sched_barrier(0)
; #define RESC(a) do { if (__any((a) < 1.f)) { if (hi == 0) al_l[r32] = (a); asm volatile("s_waitcnt lgkmcnt(0)" ::: "memory"); \
;     _Pragma("unroll") for (int d = 0; d < 4; ++d) _Pragma("unroll") for (int r = 0; r < 16; ++r) o[d][r] *= al_l[crow(r, hi)]; } } while (0)
;     ...
;   PAIR_FULL(0, 1, NP - 1);
;   { SBAR(); qkt(pB0, pB1, KSUB(1, 1), qr, r32, hi);
;     finishSM(pA0, pA1, alA, l_reg, pa0, pa1, pa2, pa3); SBAR();
;     pv_d0(o, VSUB(1, 0), pa0, pa1, pa2, pa3); partialSM(pB0, pB1, m_reg, mnB, alB);
;     RESC(alB);
;     finishSM(pB0, pB1, alB, l_reg, pa0, pa1, pa2, pa3); SBAR();
;     pv_d0(o, VSUB(1, 1), pa0, pa1, pa2, pa3); }
	v_mfma_f32_16x16x32_bf16 v[28:31], v[242:245], v[184:187], v[28:31]
	v_exp_f32_e32 v142, v142
	v_mfma_f32_16x16x32_bf16 v[60:63], v[242:245], v[192:195], v[60:63]
	ds_read_b64_tr_b16 v[230:231], v180 offset:40960
	ds_read_b64_tr_b16 v[232:233], v180 offset:45056
	v_exp_f32_e32 v143, v143
	s_waitcnt lgkmcnt(8)
	v_mfma_f32_16x16x32_bf16 v[0:3], v[200:203], v[188:191], v[0:3]
	v_exp_f32_e32 v144, v144
	v_mfma_f32_16x16x32_bf16 v[32:35], v[200:203], v[196:199], v[32:35]
	ds_read_b64_tr_b16 v[234:235], v182 offset:40960
	ds_read_b64_tr_b16 v[236:237], v182 offset:45056
	v_exp_f32_e32 v145, v145
	s_waitcnt lgkmcnt(8)
	v_mfma_f32_16x16x32_bf16 v[4:7], v[204:207], v[188:191], v[4:7]
	v_exp_f32_e32 v146, v146
	v_mfma_f32_16x16x32_bf16 v[36:39], v[204:207], v[196:199], v[36:39]
	ds_read_b64_tr_b16 v[238:239], v216 offset:40960
	ds_read_b64_tr_b16 v[240:241], v216 offset:45056
	v_exp_f32_e32 v147, v147
	s_waitcnt lgkmcnt(8)
	v_mfma_f32_16x16x32_bf16 v[8:11], v[208:211], v[188:191], v[8:11]
	v_exp_f32_e32 v148, v148
	v_mfma_f32_16x16x32_bf16 v[40:43], v[208:211], v[196:199], v[40:43]
	ds_read_b64_tr_b16 v[242:243], v217 offset:40960
	ds_read_b64_tr_b16 v[244:245], v217 offset:45056
	v_exp_f32_e32 v149, v149
	s_waitcnt lgkmcnt(8)
	v_mfma_f32_16x16x32_bf16 v[12:15], v[212:215], v[188:191], v[12:15]
	v_exp_f32_e32 v150, v150
	v_mfma_f32_16x16x32_bf16 v[44:47], v[212:215], v[196:199], v[44:47]
	v_exp_f32_e32 v151, v151
	s_waitcnt lgkmcnt(6)
	v_mfma_f32_16x16x32_bf16 v[16:19], v[230:233], v[188:191], v[16:19]
	v_exp_f32_e32 v152, v152
	v_mfma_f32_16x16x32_bf16 v[48:51], v[230:233], v[196:199], v[48:51]
	v_exp_f32_e32 v153, v153
	s_waitcnt lgkmcnt(4)
	v_mfma_f32_16x16x32_bf16 v[20:23], v[234:237], v[188:191], v[20:23]
	v_exp_f32_e32 v154, v154
	v_mfma_f32_16x16x32_bf16 v[52:55], v[234:237], v[196:199], v[52:55]
	v_exp_f32_e32 v155, v155
	s_waitcnt lgkmcnt(2)
	v_mfma_f32_16x16x32_bf16 v[24:27], v[238:241], v[188:191], v[24:27]
	v_exp_f32_e32 v156, v156
	v_mfma_f32_16x16x32_bf16 v[56:59], v[238:241], v[196:199], v[56:59]
	v_exp_f32_e32 v157, v157
	s_waitcnt lgkmcnt(0)
	v_mfma_f32_16x16x32_bf16 v[28:31], v[242:245], v[188:191], v[28:31]
	v_exp_f32_e32 v158, v158
	v_mfma_f32_16x16x32_bf16 v[60:63], v[242:245], v[196:199], v[60:63]
	v_exp_f32_e32 v159, v159
	s_waitcnt lgkmcnt(0)
	s_waitcnt vmcnt(0)
	s_barrier
	v_add_f32_e32 v169, v169, v128
	v_add_f32_e32 v169, v169, v129
	v_cvt_pk_bf16_f32 v184, v128, v129
	v_add_f32_e32 v169, v169, v130
	v_add_f32_e32 v169, v169, v131
	v_cvt_pk_bf16_f32 v185, v130, v131
	v_add_f32_e32 v222, v222, v132
	v_add_f32_e32 v222, v222, v133
	v_cvt_pk_bf16_f32 v186, v136, v137
	v_add_f32_e32 v222, v222, v134
	v_add_f32_e32 v222, v222, v135
	v_cvt_pk_bf16_f32 v187, v138, v139
	v_add_f32_e32 v169, v169, v136
	v_add_f32_e32 v169, v169, v137
	v_cvt_pk_bf16_f32 v188, v144, v145
	v_add_f32_e32 v169, v169, v138
	v_add_f32_e32 v169, v169, v139
	v_cvt_pk_bf16_f32 v189, v146, v147
	v_add_f32_e32 v222, v222, v140
	v_add_f32_e32 v222, v222, v141
	v_cvt_pk_bf16_f32 v190, v152, v153
	v_add_f32_e32 v222, v222, v142
	v_add_f32_e32 v222, v222, v143
	v_cvt_pk_bf16_f32 v191, v154, v155
	v_add_f32_e32 v169, v169, v144
	v_add_f32_e32 v169, v169, v145
	v_cvt_pk_bf16_f32 v192, v132, v133
	v_add_f32_e32 v169, v169, v146
	v_add_f32_e32 v169, v169, v147
	v_cvt_pk_bf16_f32 v193, v134, v135
	v_add_f32_e32 v222, v222, v148
	v_add_f32_e32 v222, v222, v149
	v_cvt_pk_bf16_f32 v194, v140, v141
	ds_read_b64_tr_b16 v[200:201], v176 offset:49152
	ds_read_b64_tr_b16 v[202:203], v176 offset:53248
	v_add_f32_e32 v222, v222, v150
	v_add_f32_e32 v222, v222, v151
	v_cvt_pk_bf16_f32 v195, v142, v143
	ds_read_b64_tr_b16 v[204:205], v177 offset:49152
	ds_read_b64_tr_b16 v[206:207], v177 offset:53248
	v_add_f32_e32 v169, v169, v152
	v_add_f32_e32 v169, v169, v153
	v_cvt_pk_bf16_f32 v196, v148, v149
	ds_read_b64_tr_b16 v[208:209], v178 offset:49152
	ds_read_b64_tr_b16 v[210:211], v178 offset:53248
	v_add_f32_e32 v169, v169, v154
	v_add_f32_e32 v169, v169, v155
	v_cvt_pk_bf16_f32 v197, v150, v151
	ds_read_b64_tr_b16 v[212:213], v179 offset:49152
	ds_read_b64_tr_b16 v[214:215], v179 offset:53248
	v_add_f32_e32 v222, v222, v156
	v_add_f32_e32 v222, v222, v157
	v_cvt_pk_bf16_f32 v198, v156, v157
	ds_read_b64_tr_b16 v[230:231], v180 offset:49152
	ds_read_b64_tr_b16 v[232:233], v180 offset:53248
	v_add_f32_e32 v222, v222, v158
	v_add_f32_e32 v222, v222, v159
	v_cvt_pk_bf16_f32 v199, v158, v159
	s_waitcnt lgkmcnt(8)
	v_mfma_f32_16x16x32_bf16 v[0:3], v[200:203], v[184:187], v[0:3]
	v_mfma_f32_16x16x32_bf16 v[32:35], v[200:203], v[192:195], v[32:35]
	ds_read_b64_tr_b16 v[234:235], v182 offset:49152
	ds_read_b64_tr_b16 v[236:237], v182 offset:53248
	s_waitcnt lgkmcnt(8)
	v_mfma_f32_16x16x32_bf16 v[4:7], v[204:207], v[184:187], v[4:7]
	v_mfma_f32_16x16x32_bf16 v[36:39], v[204:207], v[192:195], v[36:39]
	ds_read_b64_tr_b16 v[238:239], v216 offset:49152
	ds_read_b64_tr_b16 v[240:241], v216 offset:53248
	s_waitcnt lgkmcnt(8)
	v_mfma_f32_16x16x32_bf16 v[8:11], v[208:211], v[184:187], v[8:11]
	v_mfma_f32_16x16x32_bf16 v[40:43], v[208:211], v[192:195], v[40:43]
	ds_read_b64_tr_b16 v[242:243], v217 offset:49152
	ds_read_b64_tr_b16 v[244:245], v217 offset:53248
	s_waitcnt lgkmcnt(8)
	v_mfma_f32_16x16x32_bf16 v[12:15], v[212:215], v[184:187], v[12:15]
	v_mfma_f32_16x16x32_bf16 v[44:47], v[212:215], v[192:195], v[44:47]
	ds_read_b64_tr_b16 v[200:201], v176 offset:57344
	ds_read_b64_tr_b16 v[202:203], v176 offset:61440
	s_waitcnt lgkmcnt(8)
	v_mfma_f32_16x16x32_bf16 v[16:19], v[230:233], v[184:187], v[16:19]
	v_mfma_f32_16x16x32_bf16 v[48:51], v[230:233], v[192:195], v[48:51]
	ds_read_b64_tr_b16 v[204:205], v177 offset:57344
	ds_read_b64_tr_b16 v[206:207], v177 offset:61440
	s_waitcnt lgkmcnt(8)
; #define SBAR() __builtin_amdgcn_sched_barrier(0)
; #define RESC(a) do { if (__any((a) < 1.f)) { if (hi == 0) al_l[r32] = (a); asm volatile("s_waitcnt lgkmcnt(0)" ::: "memory"); \
;     _Pragma("unroll") for (int d = 0; d < 4; ++d) _Pragma("unroll") for (int r = 0; r < 16; ++r) o[d][r] *= al_l[crow(r, hi)]; } } while (0)
;     ...
;   PAIR_FULL(0, 1, NP - 1);
;   { SBAR(); qkt(pB0, pB1, KSUB(1, 1), qr, r32, hi);
;     finishSM(pA0, pA1, alA, l_reg, pa0, pa1, pa2, pa3); SBAR();
;     pv_d0(o, VSUB(1, 0), pa0, pa1, pa2, pa3); partialSM(pB0, pB1, m_reg, mnB, alB);
;     RESC(alB);
;     finishSM(pB0, pB1, alB, l_reg, pa0, pa1, pa2, pa3); SBAR();
;     pv_d0(o, VSUB(1, 1), pa0, pa1, pa2, pa3); }
	v_mfma_f32_16x16x32_bf16 v[20:23], v[234:237], v[184:187], v[20:23]
	v_mfma_f32_16x16x32_bf16 v[52:55], v[234:237], v[192:195], v[52:55]
	ds_read_b64_tr_b16 v[208:209], v178 offset:57344
	ds_read_b64_tr_b16 v[210:211], v178 offset:61440
	s_waitcnt lgkmcnt(8)
	v_mfma_f32_16x16x32_bf16 v[24:27], v[238:241], v[184:187], v[24:27]
	v_mfma_f32_16x16x32_bf16 v[56:59], v[238:241], v[192:195], v[56:59]
	ds_read_b64_tr_b16 v[212:213], v179 offset:57344
	ds_read_b64_tr_b16 v[214:215], v179 offset:61440
	s_waitcnt lgkmcnt(8)
	v_mfma_f32_16x16x32_bf16 v[28:31], v[242:245], v[184:187], v[28:31]
	v_mfma_f32_16x16x32_bf16 v[60:63], v[242:245], v[192:195], v[60:63]
	ds_read_b64_tr_b16 v[230:231], v180 offset:57344
	ds_read_b64_tr_b16 v[232:233], v180 offset:61440
	s_waitcnt lgkmcnt(8)
	v_mfma_f32_16x16x32_bf16 v[0:3], v[200:203], v[188:191], v[0:3]
	v_mfma_f32_16x16x32_bf16 v[32:35], v[200:203], v[196:199], v[32:35]
	ds_read_b64_tr_b16 v[234:235], v182 offset:57344
	ds_read_b64_tr_b16 v[236:237], v182 offset:61440
	s_waitcnt lgkmcnt(8)
	v_mfma_f32_16x16x32_bf16 v[4:7], v[204:207], v[188:191], v[4:7]
	v_mfma_f32_16x16x32_bf16 v[36:39], v[204:207], v[196:199], v[36:39]
	ds_read_b64_tr_b16 v[238:239], v216 offset:57344
	ds_read_b64_tr_b16 v[240:241], v216 offset:61440
	s_waitcnt lgkmcnt(8)
	v_mfma_f32_16x16x32_bf16 v[8:11], v[208:211], v[188:191], v[8:11]
	v_mfma_f32_16x16x32_bf16 v[40:43], v[208:211], v[196:199], v[40:43]
	ds_read_b64_tr_b16 v[242:243], v217 offset:57344
	ds_read_b64_tr_b16 v[244:245], v217 offset:61440
	s_waitcnt lgkmcnt(8)
	v_mfma_f32_16x16x32_bf16 v[12:15], v[212:215], v[188:191], v[12:15]
	v_mfma_f32_16x16x32_bf16 v[44:47], v[212:215], v[196:199], v[44:47]
	s_waitcnt lgkmcnt(6)
	v_mfma_f32_16x16x32_bf16 v[16:19], v[230:233], v[188:191], v[16:19]
	v_mfma_f32_16x16x32_bf16 v[48:51], v[230:233], v[196:199], v[48:51]
	s_waitcnt lgkmcnt(4)
	v_mfma_f32_16x16x32_bf16 v[20:23], v[234:237], v[188:191], v[20:23]
	v_mfma_f32_16x16x32_bf16 v[52:55], v[234:237], v[196:199], v[52:55]
	s_waitcnt lgkmcnt(2)
	v_mfma_f32_16x16x32_bf16 v[24:27], v[238:241], v[188:191], v[24:27]
	v_mfma_f32_16x16x32_bf16 v[56:59], v[238:241], v[196:199], v[56:59]
	s_waitcnt lgkmcnt(0)
	v_mfma_f32_16x16x32_bf16 v[28:31], v[242:245], v[188:191], v[28:31]
	v_mfma_f32_16x16x32_bf16 v[60:63], v[242:245], v[196:199], v[60:63]
	s_waitcnt lgkmcnt(0)
	s_waitcnt vmcnt(0)
	s_barrier
; __device__ __forceinline__ int crow(int r, int hi) { return (r & 3) + 8 * (r >> 2) + 4 * hi; }
;     ...
;   if (hi == 0) li_l[r32] = l_reg; asm volatile("s_waitcnt lgkmcnt(0)" ::: "memory");
;   if constexpr (MODE == 1) { if (hi == 0) lse_out[(long)(wid * QBLK + r32) * lse_stride] = m_reg * SCALE + __logf(l_reg); }
;   float rli[16];
; #pragma unroll
;   for (int r = 0; r < 16; ++r) rli[r] = __builtin_amdgcn_rcpf(li_l[crow(r, hi)]);
;   bf16* Ow = Ob + (long)(wid * QBLK) * ldo;
; #pragma unroll
;   for (int r = 0; r < 16; ++r) { const int orow = crow(r, hi);
; #pragma unroll
;     for (int d0 = 0; d0 < 4; ++d0) Ow[(long)orow * ldo + d0 * 32 + r32] = __float2bfloat16(o[d0][r] * rli[r]); }
;   __syncthreads();
	s_setprio 0
	v_and_b32_e32 v64, 63, v218
	v_lshlrev_b32_e32 v64, 2, v64
	v_xor_b32_e32 v65, 64, v64
	v_xor_b32_e32 v66, 0x80, v64
	ds_bpermute_b32 v67, v65, v169
	s_waitcnt lgkmcnt(0)
	v_add_f32_e32 v169, v169, v67
	ds_bpermute_b32 v67, v66, v169
	s_waitcnt lgkmcnt(0)
	v_add_f32_e32 v169, v169, v67
	v_rcp_f32_e32 v169, v169
	ds_bpermute_b32 v67, v65, v222
	s_waitcnt lgkmcnt(0)
	v_add_f32_e32 v222, v222, v67
	ds_bpermute_b32 v67, v66, v222
	s_waitcnt lgkmcnt(0)
	v_add_f32_e32 v222, v222, v67
	v_rcp_f32_e32 v222, v222
	s_lshl_b64 s[0:1], s[20:21], 12
	s_add_u32 s0, s24, s0
	s_addc_u32 s1, s25, s1
	s_lshl_b32 s2, s14, 1
	s_add_u32 s2, s0, s2
	s_addc_u32 s3, s1, 0
	s_ashr_i32 s39, s38, 31
	s_lshl_b64 s[0:1], s[38:39], 12
	s_add_u32 s0, s2, s0
	s_addc_u32 s1, s3, s1
	v_and_b32_e32 v64, 63, v218
	v_and_b32_e32 v65, 15, v64
	v_lshrrev_b32_e32 v66, 4, v64
	v_lshlrev_b32_e32 v66, 3, v66
	v_lshl_or_b32 v68, v65, 12, v66
	v_add_u32_e32 v69, 0x10000, v68
	v_mul_f32_e32 v0, v0, v169
	v_mul_f32_e32 v1, v1, v169
	v_mul_f32_e32 v2, v2, v169
	v_mul_f32_e32 v3, v3, v169
	v_cvt_pk_bf16_f32 v130, v0, v1
	v_cvt_pk_bf16_f32 v131, v2, v3
	global_store_dwordx2 v68, v[130:131], s[0:1] offset:0
	v_mul_f32_e32 v4, v4, v169
	v_mul_f32_e32 v5, v5, v169
	v_mul_f32_e32 v6, v6, v169
	v_mul_f32_e32 v7, v7, v169
	v_cvt_pk_bf16_f32 v132, v4, v5
	v_cvt_pk_bf16_f32 v133, v6, v7
	global_store_dwordx2 v68, v[132:133], s[0:1] offset:32
	v_mul_f32_e32 v8, v8, v169
	v_mul_f32_e32 v9, v9, v169
	v_mul_f32_e32 v10, v10, v169
	v_mul_f32_e32 v11, v11, v169
	v_cvt_pk_bf16_f32 v134, v8, v9
	v_cvt_pk_bf16_f32 v135, v10, v11
	global_store_dwordx2 v68, v[134:135], s[0:1] offset:64
	v_mul_f32_e32 v12, v12, v169
	v_mul_f32_e32 v13, v13, v169
	v_mul_f32_e32 v14, v14, v169
	v_mul_f32_e32 v15, v15, v169
	v_cvt_pk_bf16_f32 v136, v12, v13
	v_cvt_pk_bf16_f32 v137, v14, v15
	global_store_dwordx2 v68, v[136:137], s[0:1] offset:96
	v_mul_f32_e32 v16, v16, v169
	v_mul_f32_e32 v17, v17, v169
	v_mul_f32_e32 v18, v18, v169
	v_mul_f32_e32 v19, v19, v169
	v_cvt_pk_bf16_f32 v138, v16, v17
	v_cvt_pk_bf16_f32 v139, v18, v19
	global_store_dwordx2 v68, v[138:139], s[0:1] offset:128
	v_mul_f32_e32 v20, v20, v169
	v_mul_f32_e32 v21, v21, v169
	v_mul_f32_e32 v22, v22, v169
	v_mul_f32_e32 v23, v23, v169
	v_cvt_pk_bf16_f32 v140, v20, v21
	v_cvt_pk_bf16_f32 v141, v22, v23
	global_store_dwordx2 v68, v[140:141], s[0:1] offset:160
	v_mul_f32_e32 v24, v24, v169
	v_mul_f32_e32 v25, v25, v169
	v_mul_f32_e32 v26, v26, v169
	v_mul_f32_e32 v27, v27, v169
	v_cvt_pk_bf16_f32 v142, v24, v25
	v_cvt_pk_bf16_f32 v143, v26, v27
	global_store_dwordx2 v68, v[142:143], s[0:1] offset:192
	v_mul_f32_e32 v28, v28, v169
	v_mul_f32_e32 v29, v29, v169
	v_mul_f32_e32 v30, v30, v169
	v_mul_f32_e32 v31, v31, v169
	v_cvt_pk_bf16_f32 v144, v28, v29
	v_cvt_pk_bf16_f32 v145, v30, v31
	global_store_dwordx2 v68, v[144:145], s[0:1] offset:224
	v_mul_f32_e32 v32, v32, v222
	v_mul_f32_e32 v33, v33, v222
	v_mul_f32_e32 v34, v34, v222
	v_mul_f32_e32 v35, v35, v222
	v_cvt_pk_bf16_f32 v130, v32, v33
	v_cvt_pk_bf16_f32 v131, v34, v35
	global_store_dwordx2 v69, v[130:131], s[0:1] offset:0
	v_mul_f32_e32 v36, v36, v222
	v_mul_f32_e32 v37, v37, v222
	v_mul_f32_e32 v38, v38, v222
	v_mul_f32_e32 v39, v39, v222
	v_cvt_pk_bf16_f32 v132, v36, v37
	v_cvt_pk_bf16_f32 v133, v38, v39
	global_store_dwordx2 v69, v[132:133], s[0:1] offset:32
	v_mul_f32_e32 v40, v40, v222
	v_mul_f32_e32 v41, v41, v222
	v_mul_f32_e32 v42, v42, v222
	v_mul_f32_e32 v43, v43, v222
	v_cvt_pk_bf16_f32 v134, v40, v41
	v_cvt_pk_bf16_f32 v135, v42, v43
	global_store_dwordx2 v69, v[134:135], s[0:1] offset:64
	v_mul_f32_e32 v44, v44, v222
	v_mul_f32_e32 v45, v45, v222
	v_mul_f32_e32 v46, v46, v222
	v_mul_f32_e32 v47, v47, v222
	v_cvt_pk_bf16_f32 v136, v44, v45
	v_cvt_pk_bf16_f32 v137, v46, v47
	global_store_dwordx2 v69, v[136:137], s[0:1] offset:96
	v_mul_f32_e32 v48, v48, v222
	v_mul_f32_e32 v49, v49, v222
	v_mul_f32_e32 v50, v50, v222
	v_mul_f32_e32 v51, v51, v222
	v_cvt_pk_bf16_f32 v138, v48, v49
	v_cvt_pk_bf16_f32 v139, v50, v51
	global_store_dwordx2 v69, v[138:139], s[0:1] offset:128
	v_mul_f32_e32 v52, v52, v222
	v_mul_f32_e32 v53, v53, v222
	v_mul_f32_e32 v54, v54, v222
	v_mul_f32_e32 v55, v55, v222
	v_cvt_pk_bf16_f32 v140, v52, v53
	v_cvt_pk_bf16_f32 v141, v54, v55
	global_store_dwordx2 v69, v[140:141], s[0:1] offset:160
	v_mul_f32_e32 v56, v56, v222
	v_mul_f32_e32 v57, v57, v222
	v_mul_f32_e32 v58, v58, v222
	v_mul_f32_e32 v59, v59, v222
	v_cvt_pk_bf16_f32 v142, v56, v57
	v_cvt_pk_bf16_f32 v143, v58, v59
	global_store_dwordx2 v69, v[142:143], s[0:1] offset:192
	v_mul_f32_e32 v60, v60, v222
	v_mul_f32_e32 v61, v61, v222
	v_mul_f32_e32 v62, v62, v222
	v_mul_f32_e32 v63, v63, v222
	v_cvt_pk_bf16_f32 v144, v60, v61
	v_cvt_pk_bf16_f32 v145, v62, v63
	global_store_dwordx2 v69, v[144:145], s[0:1] offset:224
	v_lshlrev_b32_e32 v164, 4, v229
	v_mov_b32_e32 v165, 0
	s_mov_b32 s50, -1
	s_barrier
	s_branch .LBB0_478
